# FFN-up conv+SiLU epilogue: mask-free, bookkeeping-free row loop for strips with no sequence boundary (same fma order)
# speedup vs baseline: 1.0252x; 1.0012x over previous
.LBB0_640:
	s_and_b64 s[2:3], s[8:9], exec
	s_waitcnt vmcnt(0)
	v_readlane_b32 s2, v255, 15
	v_readlane_b32 s4, v255, 19
	v_readlane_b32 s3, v255, 16
	v_readlane_b32 s5, v255, 20
	s_cselect_b32 s42, s2, s4
	v_readlane_b32 s2, v255, 17
	s_cselect_b32 s28, s51, 0
	s_cselect_b32 s29, s52, 0
	s_cselect_b32 s43, s3, s5
	s_cselect_b32 s46, s2, 0
	s_cmp_lt_i32 s44, 4
	s_mov_b64 s[2:3], -1
	s_waitcnt vmcnt(0) lgkmcnt(0)
	s_barrier
	s_cbranch_scc1 .LBB0_1047
	s_cmp_lt_i32 s44, 6
	s_cbranch_scc1 .LBB0_1041
	s_cmp_gt_i32 s44, 6
	s_cbranch_scc0 .LBB0_654
	s_movk_i32 s15, 0x210
	v_lshlrev_b32_e32 v0, 3, v223
	v_mul_lo_u32 v132, v225, s15
	v_cvt_pk_bf16_f32 v131, v128, v129
	v_cvt_pk_bf16_f32 v130, v126, v127
	v_add3_u32 v0, v224, v132, v0
	v_cvt_pk_bf16_f32 v133, v124, v125
	v_cvt_pk_bf16_f32 v132, v122, v123
	ds_write2_b64 v0, v[130:131], v[132:133] offset1:4
	v_cvt_pk_bf16_f32 v131, v120, v121
	v_cvt_pk_bf16_f32 v130, v118, v119
	v_cvt_pk_bf16_f32 v133, v116, v117
	v_cvt_pk_bf16_f32 v132, v114, v115
	ds_write2_b64 v0, v[130:131], v[132:133] offset0:32 offset1:36
	v_cvt_pk_bf16_f32 v131, v112, v113
	v_cvt_pk_bf16_f32 v130, v110, v111
	v_cvt_pk_bf16_f32 v133, v108, v109
	v_cvt_pk_bf16_f32 v132, v106, v107
	v_add_u32_e32 v134, 0x2000, v0
	ds_write2_b64 v134, v[130:131], v[132:133] offset0:32 offset1:36
	v_cvt_pk_bf16_f32 v131, v104, v105
	v_cvt_pk_bf16_f32 v130, v102, v103
	v_cvt_pk_bf16_f32 v133, v100, v101
	v_cvt_pk_bf16_f32 v132, v98, v99
	ds_write2_b64 v134, v[130:131], v[132:133] offset0:64 offset1:68
	v_cvt_pk_bf16_f32 v131, v96, v97
	v_cvt_pk_bf16_f32 v130, v94, v95
	v_cvt_pk_bf16_f32 v133, v92, v93
	v_cvt_pk_bf16_f32 v132, v90, v91
	v_add_u32_e32 v134, 0x4000, v0
	ds_write2_b64 v134, v[130:131], v[132:133] offset0:64 offset1:68
	v_cvt_pk_bf16_f32 v131, v88, v89
	v_cvt_pk_bf16_f32 v130, v86, v87
	v_cvt_pk_bf16_f32 v133, v84, v85
	v_cvt_pk_bf16_f32 v132, v82, v83
	ds_write2_b64 v134, v[130:131], v[132:133] offset0:96 offset1:100
	v_cvt_pk_bf16_f32 v131, v80, v81
	v_cvt_pk_bf16_f32 v130, v78, v79
	v_cvt_pk_bf16_f32 v133, v76, v77
	v_cvt_pk_bf16_f32 v132, v74, v75
	v_add_u32_e32 v134, 0x6000, v0
	ds_write2_b64 v134, v[130:131], v[132:133] offset0:96 offset1:100
	v_cvt_pk_bf16_f32 v131, v72, v73
	v_cvt_pk_bf16_f32 v130, v70, v71
	v_cvt_pk_bf16_f32 v133, v68, v69
	v_cvt_pk_bf16_f32 v132, v66, v67
	ds_write2_b64 v134, v[130:131], v[132:133] offset0:128 offset1:132
	v_cvt_pk_bf16_f32 v131, v64, v65
	v_cvt_pk_bf16_f32 v130, v62, v63
	v_cvt_pk_bf16_f32 v133, v60, v61
	v_cvt_pk_bf16_f32 v132, v58, v59
	v_add_u32_e32 v134, 0x8000, v0
	ds_write2_b64 v134, v[130:131], v[132:133] offset0:128 offset1:132
	v_cvt_pk_bf16_f32 v131, v56, v57
	v_cvt_pk_bf16_f32 v130, v54, v55
	v_cvt_pk_bf16_f32 v133, v52, v53
	v_cvt_pk_bf16_f32 v132, v50, v51
	ds_write2_b64 v134, v[130:131], v[132:133] offset0:160 offset1:164
	v_cvt_pk_bf16_f32 v131, v48, v49
	v_cvt_pk_bf16_f32 v130, v46, v47
	v_cvt_pk_bf16_f32 v133, v44, v45
	v_cvt_pk_bf16_f32 v132, v42, v43
	v_add_u32_e32 v134, 0xa000, v0
	ds_write2_b64 v134, v[130:131], v[132:133] offset0:160 offset1:164
	v_cvt_pk_bf16_f32 v131, v36, v37
	v_cvt_pk_bf16_f32 v130, v34, v35
	v_cvt_pk_bf16_f32 v133, v32, v33
	v_cvt_pk_bf16_f32 v132, v30, v31
	ds_write2_b64 v134, v[130:131], v[132:133] offset0:192 offset1:196
	v_cvt_pk_bf16_f32 v131, v40, v41
	v_cvt_pk_bf16_f32 v130, v38, v39
	v_cvt_pk_bf16_f32 v133, v28, v29
	v_cvt_pk_bf16_f32 v132, v26, v27
	v_add_u32_e32 v134, 0xc000, v0
	ds_write2_b64 v134, v[130:131], v[132:133] offset0:192 offset1:196
	v_cvt_pk_bf16_f32 v131, v24, v25
	v_cvt_pk_bf16_f32 v130, v22, v23
	v_cvt_pk_bf16_f32 v133, v20, v21
	v_cvt_pk_bf16_f32 v132, v18, v19
	ds_write2_b64 v134, v[130:131], v[132:133] offset0:224 offset1:228
	v_cvt_pk_bf16_f32 v131, v16, v17
	v_cvt_pk_bf16_f32 v130, v14, v15
	v_cvt_pk_bf16_f32 v133, v12, v13
	v_cvt_pk_bf16_f32 v132, v10, v11
	v_add_u32_e32 v134, 0xe000, v0
	ds_write2_b64 v134, v[130:131], v[132:133] offset0:224 offset1:228
	v_cvt_pk_bf16_f32 v131, v8, v9
	v_cvt_pk_bf16_f32 v130, v6, v7
	v_cvt_pk_bf16_f32 v133, v4, v5
	v_cvt_pk_bf16_f32 v132, v2, v3
	v_add_u32_e32 v0, 0xe800, v0
	ds_write2_b64 v0, v[130:131], v[132:133] offset1:4
	v_lshlrev_b32_e32 v0, 2, v175
	v_and_b32_e32 v0, 0x7c, v0
	s_mul_i32 s2, s28, 0x10800
	v_readlane_b32 s48, v253, 61
	v_lshl_or_b32 v164, s47, 7, v0
	s_mul_hi_u32 s3, s28, 0x10800
	v_readlane_b32 s49, v253, 62
	s_add_u32 s2, s48, s2
	v_ashrrev_i32_e32 v165, 31, v164
	s_addc_u32 s3, s49, s3
	v_lshlrev_b64 v[130:131], 2, v[164:165]
	v_lshl_add_u64 v[150:151], s[2:3], 0, v[130:131]
	s_movk_i32 s2, 0x5000
	v_add_co_u32_e32 v134, vcc, s2, v150
	s_mov_b32 s2, 0xb000
	s_nop 0
	v_addc_co_u32_e32 v135, vcc, 0, v151, vcc
	v_add_co_u32_e32 v138, vcc, s2, v150
	v_readlane_b32 s50, v253, 63
	s_nop 0
	v_addc_co_u32_e32 v139, vcc, 0, v151, vcc
	v_add_co_u32_e32 v142, vcc, s25, v150
	s_mul_i32 s4, s28, 0x5800
	s_nop 0
	v_addc_co_u32_e32 v143, vcc, 0, v151, vcc
	s_mov_b32 s2, 0x8000
	v_readlane_b32 s51, v254, 0
	s_mul_hi_u32 s5, s28, 0x5800
	s_add_u32 s4, s50, s4
	v_add_co_u32_e32 v146, vcc, s2, v150
	s_addc_u32 s5, s51, s5
	s_nop 0
	v_addc_co_u32_e32 v147, vcc, 0, v151, vcc
	s_mov_b32 s2, 0xd000
	s_waitcnt lgkmcnt(0)
	s_barrier
	v_lshl_add_u64 v[158:159], s[4:5], 0, v[130:131]
	global_load_dwordx4 v[130:133], v[150:151], off
	v_add_co_u32_e32 v150, vcc, s2, v150
	global_load_dwordx4 v[134:137], v[134:135], off offset:2048
	s_nop 0
	global_load_dwordx4 v[138:141], v[138:139], off
	v_addc_co_u32_e32 v151, vcc, 0, v151, vcc
	global_load_dwordx4 v[142:145], v[142:143], off offset:3072
	s_nop 0
	global_load_dwordx4 v[146:149], v[146:147], off offset:1024
	s_nop 0
	global_load_dwordx4 v[150:153], v[150:151], off offset:3072
	s_nop 0
	global_load_dwordx4 v[154:157], v[158:159], off
	v_add_co_u32_e32 v158, vcc, 0x2000, v158
	v_ashrrev_i32_e32 v0, 5, v175
	s_nop 0
	v_addc_co_u32_e32 v159, vcc, 0, v159, vcc
	global_load_dwordx4 v[158:161], v[158:159], off offset:3072
	v_readlane_b32 s2, v252, 32
	v_readlane_b32 s3, v252, 33
	v_mul_lo_u32 v166, v0, s15
	v_and_b32_e32 v167, 31, v175
	s_mov_b32 s14, 0
	v_lshl_add_u64 v[164:165], v[164:165], 1, s[2:3]
	v_lshl_add_u32 v166, v167, 3, v166
	v_add_u32_e32 v167, s40, v0
	s_waitcnt vmcnt(0)
	s_mov_b32 s14, 0x8800
	v_mul_u32_u24_e32 v63, 0x2100, v0
	v_and_b32_e32 v64, 31, v175
	v_lshl_add_u32 v63, v64, 3, v63
	v_lshlrev_b32_e32 v61, 4, v0
	v_add_u32_e32 v61, 1, v61
	v_add_u32_e32 v62, s40, v61
	s_mov_b32 s4, 0x78787879
	v_mul_hi_i32 v60, v62, s4
	v_lshrrev_b32_e32 v64, 31, v60
	v_ashrrev_i32_e32 v60, 11, v60
	v_add_u32_e32 v60, v60, v64
	v_mul_i32_i24_e32 v60, 0x1100, v60
	v_sub_u32_e32 v60, v62, v60
	s_movk_i32 s4, 0x1600
	v_mad_i64_i32 v[58:59], s[4:5], v62, s4, v[164:165]
	v_mov_b32_e32 v56, 0x1600
	v_mov_b32_e32 v57, 0
	ds_read2_b64 v[26:29], v63 offset1:32
	ds_read2_b64 v[68:71], v63 offset0:66 offset1:98
	s_waitcnt lgkmcnt(0)
	v_lshlrev_b32_e32 v2, 16, v26
	v_and_b32_e32 v3, 0xffff0000, v26
	v_lshlrev_b32_e32 v4, 16, v27
	v_and_b32_e32 v5, 0xffff0000, v27
	v_lshlrev_b32_e32 v14, 16, v28
	v_and_b32_e32 v15, 0xffff0000, v28
	v_lshlrev_b32_e32 v16, 16, v29
	v_and_b32_e32 v17, 0xffff0000, v29
	v_lshlrev_b32_e32 v6, 16, v68
	v_and_b32_e32 v7, 0xffff0000, v68
	v_lshlrev_b32_e32 v8, 16, v69
	v_and_b32_e32 v9, 0xffff0000, v69
	v_lshlrev_b32_e32 v18, 16, v70
	v_and_b32_e32 v19, 0xffff0000, v70
	v_lshlrev_b32_e32 v20, 16, v71
	v_and_b32_e32 v21, 0xffff0000, v71
	v_add_u32_e32 v63, 0x420, v63
	v_add_u32_e32 v64, -1, v60
	v_add_u32_e32 v65, 0xfffffeff, v60
	v_cmp_gt_u32_e32 vcc, 0xfef, v65
	s_mov_b64 s[4:5], vcc
	v_cmp_gt_u32_e32 vcc, 0xef, v64
	s_or_b64 s[4:5], s[4:5], vcc
	v_cmp_gt_u32_e32 vcc, 15, v0
	s_and_b64 s[4:5], s[4:5], vcc
	v_add_u32_e32 v64, 15, v62
	v_cmp_gt_i32_e32 vcc, s14, v64
	s_and_b64 s[4:5], s[4:5], vcc
	s_xor_b64 s[4:5], s[4:5], exec
	s_cmp_eq_u64 s[4:5], 0
	s_cbranch_scc0 .Lconv_slow
	ds_read2_b64 v[26:29], v63 offset1:32
	s_waitcnt lgkmcnt(0)
	v_lshlrev_b32_e32 v10, 16, v26
	v_and_b32_e32 v11, 0xffff0000, v26
	v_lshlrev_b32_e32 v12, 16, v27
	v_and_b32_e32 v13, 0xffff0000, v27
	v_lshlrev_b32_e32 v22, 16, v28
	v_and_b32_e32 v23, 0xffff0000, v28
	v_lshlrev_b32_e32 v24, 16, v29
	v_and_b32_e32 v25, 0xffff0000, v29
	v_add_u32_e32 v63, 0x210, v63
	ds_read2_b64 v[26:29], v63 offset1:32
	v_pk_fma_f32 v[30:31], v[146:147], v[18:19], v[158:159]
	v_pk_fma_f32 v[32:33], v[148:149], v[20:21], v[160:161]
	v_pk_fma_f32 v[34:35], v[134:135], v[6:7], v[154:155]
	v_pk_fma_f32 v[36:37], v[136:137], v[8:9], v[156:157]
	v_pk_fma_f32 v[30:31], v[142:143], v[14:15], v[30:31]
	v_pk_fma_f32 v[32:33], v[144:145], v[16:17], v[32:33]
	v_pk_fma_f32 v[34:35], v[130:131], v[2:3], v[34:35]
	v_pk_fma_f32 v[36:37], v[132:133], v[4:5], v[36:37]
	v_pk_fma_f32 v[30:31], v[150:151], v[22:23], v[30:31]
	v_pk_fma_f32 v[32:33], v[152:153], v[24:25], v[32:33]
	v_pk_fma_f32 v[34:35], v[138:139], v[10:11], v[34:35]
	v_pk_fma_f32 v[36:37], v[140:141], v[12:13], v[36:37]
	v_mul_f32_e32 v42, 0xbfb8aa3b, v30
	v_mul_f32_e32 v43, 0xbfb8aa3b, v31
	v_mul_f32_e32 v44, 0xbfb8aa3b, v32
	v_mul_f32_e32 v45, 0xbfb8aa3b, v33
	v_exp_f32_e32 v42, v42
	v_exp_f32_e32 v43, v43
	v_exp_f32_e32 v44, v44
	v_exp_f32_e32 v45, v45
	v_pk_add_f32 v[42:43], v[42:43], 1.0 op_sel_hi:[1,0]
	v_pk_add_f32 v[44:45], v[44:45], 1.0 op_sel_hi:[1,0]
	v_rcp_f32_e32 v46, v42
	v_rcp_f32_e32 v47, v43
	v_rcp_f32_e32 v48, v44
	v_rcp_f32_e32 v49, v45
	v_mul_f32_e32 v46, v30, v46
	v_mul_f32_e32 v47, v31, v47
	v_mul_f32_e32 v48, v32, v48
	v_mul_f32_e32 v49, v33, v49
	v_pk_mul_f32 v[34:35], v[34:35], v[46:47]
	v_pk_mul_f32 v[36:37], v[36:37], v[48:49]
	v_cvt_pk_bf16_f32 v66, v34, v35
	v_cvt_pk_bf16_f32 v67, v36, v37
	global_store_dwordx2 v[58:59], v[66:67], off
	v_lshl_add_u64 v[58:59], v[58:59], 0, v[56:57]
	s_waitcnt lgkmcnt(0)
	v_lshlrev_b32_e32 v2, 16, v26
	v_and_b32_e32 v3, 0xffff0000, v26
	v_lshlrev_b32_e32 v4, 16, v27
	v_and_b32_e32 v5, 0xffff0000, v27
	v_lshlrev_b32_e32 v14, 16, v28
	v_and_b32_e32 v15, 0xffff0000, v28
	v_lshlrev_b32_e32 v16, 16, v29
	v_and_b32_e32 v17, 0xffff0000, v29
	v_add_u32_e32 v63, 0x210, v63
	ds_read2_b64 v[26:29], v63 offset1:32
	v_pk_fma_f32 v[30:31], v[146:147], v[22:23], v[158:159]
	v_pk_fma_f32 v[32:33], v[148:149], v[24:25], v[160:161]
	v_pk_fma_f32 v[34:35], v[134:135], v[10:11], v[154:155]
	v_pk_fma_f32 v[36:37], v[136:137], v[12:13], v[156:157]
	v_pk_fma_f32 v[30:31], v[142:143], v[18:19], v[30:31]
	v_pk_fma_f32 v[32:33], v[144:145], v[20:21], v[32:33]
	v_pk_fma_f32 v[34:35], v[130:131], v[6:7], v[34:35]
	v_pk_fma_f32 v[36:37], v[132:133], v[8:9], v[36:37]
	v_pk_fma_f32 v[30:31], v[150:151], v[14:15], v[30:31]
	v_pk_fma_f32 v[32:33], v[152:153], v[16:17], v[32:33]
	v_pk_fma_f32 v[34:35], v[138:139], v[2:3], v[34:35]
	v_pk_fma_f32 v[36:37], v[140:141], v[4:5], v[36:37]
	v_mul_f32_e32 v42, 0xbfb8aa3b, v30
	v_mul_f32_e32 v43, 0xbfb8aa3b, v31
	v_mul_f32_e32 v44, 0xbfb8aa3b, v32
	v_mul_f32_e32 v45, 0xbfb8aa3b, v33
	v_exp_f32_e32 v42, v42
	v_exp_f32_e32 v43, v43
	v_exp_f32_e32 v44, v44
	v_exp_f32_e32 v45, v45
	v_pk_add_f32 v[42:43], v[42:43], 1.0 op_sel_hi:[1,0]
	v_pk_add_f32 v[44:45], v[44:45], 1.0 op_sel_hi:[1,0]
	v_rcp_f32_e32 v46, v42
	v_rcp_f32_e32 v47, v43
	v_rcp_f32_e32 v48, v44
	v_rcp_f32_e32 v49, v45
	v_mul_f32_e32 v46, v30, v46
	v_mul_f32_e32 v47, v31, v47
	v_mul_f32_e32 v48, v32, v48
	v_mul_f32_e32 v49, v33, v49
	v_pk_mul_f32 v[34:35], v[34:35], v[46:47]
	v_pk_mul_f32 v[36:37], v[36:37], v[48:49]
	v_cvt_pk_bf16_f32 v66, v34, v35
	v_cvt_pk_bf16_f32 v67, v36, v37
	global_store_dwordx2 v[58:59], v[66:67], off
	v_lshl_add_u64 v[58:59], v[58:59], 0, v[56:57]
	s_waitcnt lgkmcnt(0)
	v_lshlrev_b32_e32 v6, 16, v26
	v_and_b32_e32 v7, 0xffff0000, v26
	v_lshlrev_b32_e32 v8, 16, v27
	v_and_b32_e32 v9, 0xffff0000, v27
	v_lshlrev_b32_e32 v18, 16, v28
	v_and_b32_e32 v19, 0xffff0000, v28
	v_lshlrev_b32_e32 v20, 16, v29
	v_and_b32_e32 v21, 0xffff0000, v29
	v_add_u32_e32 v63, 0x210, v63
	ds_read2_b64 v[26:29], v63 offset1:32
	v_pk_fma_f32 v[30:31], v[146:147], v[14:15], v[158:159]
	v_pk_fma_f32 v[32:33], v[148:149], v[16:17], v[160:161]
	v_pk_fma_f32 v[34:35], v[134:135], v[2:3], v[154:155]
	v_pk_fma_f32 v[36:37], v[136:137], v[4:5], v[156:157]
	v_pk_fma_f32 v[30:31], v[142:143], v[22:23], v[30:31]
	v_pk_fma_f32 v[32:33], v[144:145], v[24:25], v[32:33]
	v_pk_fma_f32 v[34:35], v[130:131], v[10:11], v[34:35]
	v_pk_fma_f32 v[36:37], v[132:133], v[12:13], v[36:37]
	v_pk_fma_f32 v[30:31], v[150:151], v[18:19], v[30:31]
	v_pk_fma_f32 v[32:33], v[152:153], v[20:21], v[32:33]
	v_pk_fma_f32 v[34:35], v[138:139], v[6:7], v[34:35]
	v_pk_fma_f32 v[36:37], v[140:141], v[8:9], v[36:37]
	v_mul_f32_e32 v42, 0xbfb8aa3b, v30
	v_mul_f32_e32 v43, 0xbfb8aa3b, v31
	v_mul_f32_e32 v44, 0xbfb8aa3b, v32
	v_mul_f32_e32 v45, 0xbfb8aa3b, v33
	v_exp_f32_e32 v42, v42
	v_exp_f32_e32 v43, v43
	v_exp_f32_e32 v44, v44
	v_exp_f32_e32 v45, v45
	v_pk_add_f32 v[42:43], v[42:43], 1.0 op_sel_hi:[1,0]
	v_pk_add_f32 v[44:45], v[44:45], 1.0 op_sel_hi:[1,0]
	v_rcp_f32_e32 v46, v42
	v_rcp_f32_e32 v47, v43
	v_rcp_f32_e32 v48, v44
	v_rcp_f32_e32 v49, v45
	v_mul_f32_e32 v46, v30, v46
	v_mul_f32_e32 v47, v31, v47
	v_mul_f32_e32 v48, v32, v48
	v_mul_f32_e32 v49, v33, v49
	v_pk_mul_f32 v[34:35], v[34:35], v[46:47]
	v_pk_mul_f32 v[36:37], v[36:37], v[48:49]
	v_cvt_pk_bf16_f32 v66, v34, v35
	v_cvt_pk_bf16_f32 v67, v36, v37
	global_store_dwordx2 v[58:59], v[66:67], off
	v_lshl_add_u64 v[58:59], v[58:59], 0, v[56:57]
	s_waitcnt lgkmcnt(0)
	v_lshlrev_b32_e32 v10, 16, v26
	v_and_b32_e32 v11, 0xffff0000, v26
	v_lshlrev_b32_e32 v12, 16, v27
	v_and_b32_e32 v13, 0xffff0000, v27
	v_lshlrev_b32_e32 v22, 16, v28
	v_and_b32_e32 v23, 0xffff0000, v28
	v_lshlrev_b32_e32 v24, 16, v29
	v_and_b32_e32 v25, 0xffff0000, v29
	v_add_u32_e32 v63, 0x210, v63
	ds_read2_b64 v[26:29], v63 offset1:32
	v_pk_fma_f32 v[30:31], v[146:147], v[18:19], v[158:159]
	v_pk_fma_f32 v[32:33], v[148:149], v[20:21], v[160:161]
	v_pk_fma_f32 v[34:35], v[134:135], v[6:7], v[154:155]
	v_pk_fma_f32 v[36:37], v[136:137], v[8:9], v[156:157]
	v_pk_fma_f32 v[30:31], v[142:143], v[14:15], v[30:31]
	v_pk_fma_f32 v[32:33], v[144:145], v[16:17], v[32:33]
	v_pk_fma_f32 v[34:35], v[130:131], v[2:3], v[34:35]
	v_pk_fma_f32 v[36:37], v[132:133], v[4:5], v[36:37]
	v_pk_fma_f32 v[30:31], v[150:151], v[22:23], v[30:31]
	v_pk_fma_f32 v[32:33], v[152:153], v[24:25], v[32:33]
	v_pk_fma_f32 v[34:35], v[138:139], v[10:11], v[34:35]
	v_pk_fma_f32 v[36:37], v[140:141], v[12:13], v[36:37]
	v_mul_f32_e32 v42, 0xbfb8aa3b, v30
	v_mul_f32_e32 v43, 0xbfb8aa3b, v31
	v_mul_f32_e32 v44, 0xbfb8aa3b, v32
	v_mul_f32_e32 v45, 0xbfb8aa3b, v33
	v_exp_f32_e32 v42, v42
	v_exp_f32_e32 v43, v43
	v_exp_f32_e32 v44, v44
	v_exp_f32_e32 v45, v45
	v_pk_add_f32 v[42:43], v[42:43], 1.0 op_sel_hi:[1,0]
	v_pk_add_f32 v[44:45], v[44:45], 1.0 op_sel_hi:[1,0]
	v_rcp_f32_e32 v46, v42
	v_rcp_f32_e32 v47, v43
	v_rcp_f32_e32 v48, v44
	v_rcp_f32_e32 v49, v45
	v_mul_f32_e32 v46, v30, v46
	v_mul_f32_e32 v47, v31, v47
	v_mul_f32_e32 v48, v32, v48
	v_mul_f32_e32 v49, v33, v49
	v_pk_mul_f32 v[34:35], v[34:35], v[46:47]
	v_pk_mul_f32 v[36:37], v[36:37], v[48:49]
	v_cvt_pk_bf16_f32 v66, v34, v35
	v_cvt_pk_bf16_f32 v67, v36, v37
	global_store_dwordx2 v[58:59], v[66:67], off
	v_lshl_add_u64 v[58:59], v[58:59], 0, v[56:57]
	s_waitcnt lgkmcnt(0)
	v_lshlrev_b32_e32 v2, 16, v26
	v_and_b32_e32 v3, 0xffff0000, v26
	v_lshlrev_b32_e32 v4, 16, v27
	v_and_b32_e32 v5, 0xffff0000, v27
	v_lshlrev_b32_e32 v14, 16, v28
	v_and_b32_e32 v15, 0xffff0000, v28
	v_lshlrev_b32_e32 v16, 16, v29
	v_and_b32_e32 v17, 0xffff0000, v29
	v_add_u32_e32 v63, 0x210, v63
	ds_read2_b64 v[26:29], v63 offset1:32
	v_pk_fma_f32 v[30:31], v[146:147], v[22:23], v[158:159]
	v_pk_fma_f32 v[32:33], v[148:149], v[24:25], v[160:161]
	v_pk_fma_f32 v[34:35], v[134:135], v[10:11], v[154:155]
	v_pk_fma_f32 v[36:37], v[136:137], v[12:13], v[156:157]
	v_pk_fma_f32 v[30:31], v[142:143], v[18:19], v[30:31]
	v_pk_fma_f32 v[32:33], v[144:145], v[20:21], v[32:33]
	v_pk_fma_f32 v[34:35], v[130:131], v[6:7], v[34:35]
	v_pk_fma_f32 v[36:37], v[132:133], v[8:9], v[36:37]
	v_pk_fma_f32 v[30:31], v[150:151], v[14:15], v[30:31]
	v_pk_fma_f32 v[32:33], v[152:153], v[16:17], v[32:33]
	v_pk_fma_f32 v[34:35], v[138:139], v[2:3], v[34:35]
	v_pk_fma_f32 v[36:37], v[140:141], v[4:5], v[36:37]
	v_mul_f32_e32 v42, 0xbfb8aa3b, v30
	v_mul_f32_e32 v43, 0xbfb8aa3b, v31
	v_mul_f32_e32 v44, 0xbfb8aa3b, v32
	v_mul_f32_e32 v45, 0xbfb8aa3b, v33
	v_exp_f32_e32 v42, v42
	v_exp_f32_e32 v43, v43
	v_exp_f32_e32 v44, v44
	v_exp_f32_e32 v45, v45
	v_pk_add_f32 v[42:43], v[42:43], 1.0 op_sel_hi:[1,0]
	v_pk_add_f32 v[44:45], v[44:45], 1.0 op_sel_hi:[1,0]
	v_rcp_f32_e32 v46, v42
	v_rcp_f32_e32 v47, v43
	v_rcp_f32_e32 v48, v44
	v_rcp_f32_e32 v49, v45
	v_mul_f32_e32 v46, v30, v46
	v_mul_f32_e32 v47, v31, v47
	v_mul_f32_e32 v48, v32, v48
	v_mul_f32_e32 v49, v33, v49
	v_pk_mul_f32 v[34:35], v[34:35], v[46:47]
	v_pk_mul_f32 v[36:37], v[36:37], v[48:49]
	v_cvt_pk_bf16_f32 v66, v34, v35
	v_cvt_pk_bf16_f32 v67, v36, v37
	global_store_dwordx2 v[58:59], v[66:67], off
	v_lshl_add_u64 v[58:59], v[58:59], 0, v[56:57]
	s_waitcnt lgkmcnt(0)
	v_lshlrev_b32_e32 v6, 16, v26
	v_and_b32_e32 v7, 0xffff0000, v26
	v_lshlrev_b32_e32 v8, 16, v27
	v_and_b32_e32 v9, 0xffff0000, v27
	v_lshlrev_b32_e32 v18, 16, v28
	v_and_b32_e32 v19, 0xffff0000, v28
	v_lshlrev_b32_e32 v20, 16, v29
	v_and_b32_e32 v21, 0xffff0000, v29
	v_add_u32_e32 v63, 0x210, v63
	ds_read2_b64 v[26:29], v63 offset1:32
	v_pk_fma_f32 v[30:31], v[146:147], v[14:15], v[158:159]
	v_pk_fma_f32 v[32:33], v[148:149], v[16:17], v[160:161]
	v_pk_fma_f32 v[34:35], v[134:135], v[2:3], v[154:155]
	v_pk_fma_f32 v[36:37], v[136:137], v[4:5], v[156:157]
	v_pk_fma_f32 v[30:31], v[142:143], v[22:23], v[30:31]
	v_pk_fma_f32 v[32:33], v[144:145], v[24:25], v[32:33]
	v_pk_fma_f32 v[34:35], v[130:131], v[10:11], v[34:35]
	v_pk_fma_f32 v[36:37], v[132:133], v[12:13], v[36:37]
	v_pk_fma_f32 v[30:31], v[150:151], v[18:19], v[30:31]
	v_pk_fma_f32 v[32:33], v[152:153], v[20:21], v[32:33]
	v_pk_fma_f32 v[34:35], v[138:139], v[6:7], v[34:35]
	v_pk_fma_f32 v[36:37], v[140:141], v[8:9], v[36:37]
	v_mul_f32_e32 v42, 0xbfb8aa3b, v30
	v_mul_f32_e32 v43, 0xbfb8aa3b, v31
	v_mul_f32_e32 v44, 0xbfb8aa3b, v32
	v_mul_f32_e32 v45, 0xbfb8aa3b, v33
	v_exp_f32_e32 v42, v42
	v_exp_f32_e32 v43, v43
	v_exp_f32_e32 v44, v44
	v_exp_f32_e32 v45, v45
	v_pk_add_f32 v[42:43], v[42:43], 1.0 op_sel_hi:[1,0]
	v_pk_add_f32 v[44:45], v[44:45], 1.0 op_sel_hi:[1,0]
	v_rcp_f32_e32 v46, v42
	v_rcp_f32_e32 v47, v43
	v_rcp_f32_e32 v48, v44
	v_rcp_f32_e32 v49, v45
	v_mul_f32_e32 v46, v30, v46
	v_mul_f32_e32 v47, v31, v47
	v_mul_f32_e32 v48, v32, v48
	v_mul_f32_e32 v49, v33, v49
	v_pk_mul_f32 v[34:35], v[34:35], v[46:47]
	v_pk_mul_f32 v[36:37], v[36:37], v[48:49]
	v_cvt_pk_bf16_f32 v66, v34, v35
	v_cvt_pk_bf16_f32 v67, v36, v37
	global_store_dwordx2 v[58:59], v[66:67], off
	v_lshl_add_u64 v[58:59], v[58:59], 0, v[56:57]
	s_waitcnt lgkmcnt(0)
	v_lshlrev_b32_e32 v10, 16, v26
	v_and_b32_e32 v11, 0xffff0000, v26
	v_lshlrev_b32_e32 v12, 16, v27
	v_and_b32_e32 v13, 0xffff0000, v27
	v_lshlrev_b32_e32 v22, 16, v28
	v_and_b32_e32 v23, 0xffff0000, v28
	v_lshlrev_b32_e32 v24, 16, v29
	v_and_b32_e32 v25, 0xffff0000, v29
	v_add_u32_e32 v63, 0x210, v63
	ds_read2_b64 v[26:29], v63 offset1:32
	v_pk_fma_f32 v[30:31], v[146:147], v[18:19], v[158:159]
	v_pk_fma_f32 v[32:33], v[148:149], v[20:21], v[160:161]
	v_pk_fma_f32 v[34:35], v[134:135], v[6:7], v[154:155]
	v_pk_fma_f32 v[36:37], v[136:137], v[8:9], v[156:157]
	v_pk_fma_f32 v[30:31], v[142:143], v[14:15], v[30:31]
	v_pk_fma_f32 v[32:33], v[144:145], v[16:17], v[32:33]
	v_pk_fma_f32 v[34:35], v[130:131], v[2:3], v[34:35]
	v_pk_fma_f32 v[36:37], v[132:133], v[4:5], v[36:37]
	v_pk_fma_f32 v[30:31], v[150:151], v[22:23], v[30:31]
	v_pk_fma_f32 v[32:33], v[152:153], v[24:25], v[32:33]
	v_pk_fma_f32 v[34:35], v[138:139], v[10:11], v[34:35]
	v_pk_fma_f32 v[36:37], v[140:141], v[12:13], v[36:37]
	v_mul_f32_e32 v42, 0xbfb8aa3b, v30
	v_mul_f32_e32 v43, 0xbfb8aa3b, v31
	v_mul_f32_e32 v44, 0xbfb8aa3b, v32
	v_mul_f32_e32 v45, 0xbfb8aa3b, v33
	v_exp_f32_e32 v42, v42
	v_exp_f32_e32 v43, v43
	v_exp_f32_e32 v44, v44
	v_exp_f32_e32 v45, v45
	v_pk_add_f32 v[42:43], v[42:43], 1.0 op_sel_hi:[1,0]
	v_pk_add_f32 v[44:45], v[44:45], 1.0 op_sel_hi:[1,0]
	v_rcp_f32_e32 v46, v42
	v_rcp_f32_e32 v47, v43
	v_rcp_f32_e32 v48, v44
	v_rcp_f32_e32 v49, v45
	v_mul_f32_e32 v46, v30, v46
	v_mul_f32_e32 v47, v31, v47
	v_mul_f32_e32 v48, v32, v48
	v_mul_f32_e32 v49, v33, v49
	v_pk_mul_f32 v[34:35], v[34:35], v[46:47]
	v_pk_mul_f32 v[36:37], v[36:37], v[48:49]
	v_cvt_pk_bf16_f32 v66, v34, v35
	v_cvt_pk_bf16_f32 v67, v36, v37
	global_store_dwordx2 v[58:59], v[66:67], off
	v_lshl_add_u64 v[58:59], v[58:59], 0, v[56:57]
	s_waitcnt lgkmcnt(0)
	v_lshlrev_b32_e32 v2, 16, v26
	v_and_b32_e32 v3, 0xffff0000, v26
	v_lshlrev_b32_e32 v4, 16, v27
	v_and_b32_e32 v5, 0xffff0000, v27
	v_lshlrev_b32_e32 v14, 16, v28
	v_and_b32_e32 v15, 0xffff0000, v28
	v_lshlrev_b32_e32 v16, 16, v29
	v_and_b32_e32 v17, 0xffff0000, v29
	v_add_u32_e32 v63, 0x210, v63
	ds_read2_b64 v[26:29], v63 offset1:32
	v_pk_fma_f32 v[30:31], v[146:147], v[22:23], v[158:159]
	v_pk_fma_f32 v[32:33], v[148:149], v[24:25], v[160:161]
	v_pk_fma_f32 v[34:35], v[134:135], v[10:11], v[154:155]
	v_pk_fma_f32 v[36:37], v[136:137], v[12:13], v[156:157]
	v_pk_fma_f32 v[30:31], v[142:143], v[18:19], v[30:31]
	v_pk_fma_f32 v[32:33], v[144:145], v[20:21], v[32:33]
	v_pk_fma_f32 v[34:35], v[130:131], v[6:7], v[34:35]
	v_pk_fma_f32 v[36:37], v[132:133], v[8:9], v[36:37]
	v_pk_fma_f32 v[30:31], v[150:151], v[14:15], v[30:31]
	v_pk_fma_f32 v[32:33], v[152:153], v[16:17], v[32:33]
	v_pk_fma_f32 v[34:35], v[138:139], v[2:3], v[34:35]
	v_pk_fma_f32 v[36:37], v[140:141], v[4:5], v[36:37]
	v_mul_f32_e32 v42, 0xbfb8aa3b, v30
	v_mul_f32_e32 v43, 0xbfb8aa3b, v31
	v_mul_f32_e32 v44, 0xbfb8aa3b, v32
	v_mul_f32_e32 v45, 0xbfb8aa3b, v33
	v_exp_f32_e32 v42, v42
	v_exp_f32_e32 v43, v43
	v_exp_f32_e32 v44, v44
	v_exp_f32_e32 v45, v45
	v_pk_add_f32 v[42:43], v[42:43], 1.0 op_sel_hi:[1,0]
	v_pk_add_f32 v[44:45], v[44:45], 1.0 op_sel_hi:[1,0]
	v_rcp_f32_e32 v46, v42
	v_rcp_f32_e32 v47, v43
	v_rcp_f32_e32 v48, v44
	v_rcp_f32_e32 v49, v45
	v_mul_f32_e32 v46, v30, v46
	v_mul_f32_e32 v47, v31, v47
	v_mul_f32_e32 v48, v32, v48
	v_mul_f32_e32 v49, v33, v49
	v_pk_mul_f32 v[34:35], v[34:35], v[46:47]
	v_pk_mul_f32 v[36:37], v[36:37], v[48:49]
	v_cvt_pk_bf16_f32 v66, v34, v35
	v_cvt_pk_bf16_f32 v67, v36, v37
	global_store_dwordx2 v[58:59], v[66:67], off
	v_lshl_add_u64 v[58:59], v[58:59], 0, v[56:57]
	s_waitcnt lgkmcnt(0)
	v_lshlrev_b32_e32 v6, 16, v26
	v_and_b32_e32 v7, 0xffff0000, v26
	v_lshlrev_b32_e32 v8, 16, v27
	v_and_b32_e32 v9, 0xffff0000, v27
	v_lshlrev_b32_e32 v18, 16, v28
	v_and_b32_e32 v19, 0xffff0000, v28
	v_lshlrev_b32_e32 v20, 16, v29
	v_and_b32_e32 v21, 0xffff0000, v29
	v_add_u32_e32 v63, 0x210, v63
	ds_read2_b64 v[26:29], v63 offset1:32
	v_pk_fma_f32 v[30:31], v[146:147], v[14:15], v[158:159]
	v_pk_fma_f32 v[32:33], v[148:149], v[16:17], v[160:161]
	v_pk_fma_f32 v[34:35], v[134:135], v[2:3], v[154:155]
	v_pk_fma_f32 v[36:37], v[136:137], v[4:5], v[156:157]
	v_pk_fma_f32 v[30:31], v[142:143], v[22:23], v[30:31]
	v_pk_fma_f32 v[32:33], v[144:145], v[24:25], v[32:33]
	v_pk_fma_f32 v[34:35], v[130:131], v[10:11], v[34:35]
	v_pk_fma_f32 v[36:37], v[132:133], v[12:13], v[36:37]
	v_pk_fma_f32 v[30:31], v[150:151], v[18:19], v[30:31]
	v_pk_fma_f32 v[32:33], v[152:153], v[20:21], v[32:33]
	v_pk_fma_f32 v[34:35], v[138:139], v[6:7], v[34:35]
	v_pk_fma_f32 v[36:37], v[140:141], v[8:9], v[36:37]
	v_mul_f32_e32 v42, 0xbfb8aa3b, v30
	v_mul_f32_e32 v43, 0xbfb8aa3b, v31
	v_mul_f32_e32 v44, 0xbfb8aa3b, v32
	v_mul_f32_e32 v45, 0xbfb8aa3b, v33
	v_exp_f32_e32 v42, v42
	v_exp_f32_e32 v43, v43
	v_exp_f32_e32 v44, v44
	v_exp_f32_e32 v45, v45
	v_pk_add_f32 v[42:43], v[42:43], 1.0 op_sel_hi:[1,0]
	v_pk_add_f32 v[44:45], v[44:45], 1.0 op_sel_hi:[1,0]
	v_rcp_f32_e32 v46, v42
	v_rcp_f32_e32 v47, v43
	v_rcp_f32_e32 v48, v44
	v_rcp_f32_e32 v49, v45
	v_mul_f32_e32 v46, v30, v46
	v_mul_f32_e32 v47, v31, v47
	v_mul_f32_e32 v48, v32, v48
	v_mul_f32_e32 v49, v33, v49
	v_pk_mul_f32 v[34:35], v[34:35], v[46:47]
	v_pk_mul_f32 v[36:37], v[36:37], v[48:49]
	v_cvt_pk_bf16_f32 v66, v34, v35
	v_cvt_pk_bf16_f32 v67, v36, v37
	global_store_dwordx2 v[58:59], v[66:67], off
	v_lshl_add_u64 v[58:59], v[58:59], 0, v[56:57]
	s_waitcnt lgkmcnt(0)
	v_lshlrev_b32_e32 v10, 16, v26
	v_and_b32_e32 v11, 0xffff0000, v26
	v_lshlrev_b32_e32 v12, 16, v27
	v_and_b32_e32 v13, 0xffff0000, v27
	v_lshlrev_b32_e32 v22, 16, v28
	v_and_b32_e32 v23, 0xffff0000, v28
	v_lshlrev_b32_e32 v24, 16, v29
	v_and_b32_e32 v25, 0xffff0000, v29
	v_add_u32_e32 v63, 0x210, v63
	ds_read2_b64 v[26:29], v63 offset1:32
	v_pk_fma_f32 v[30:31], v[146:147], v[18:19], v[158:159]
	v_pk_fma_f32 v[32:33], v[148:149], v[20:21], v[160:161]
	v_pk_fma_f32 v[34:35], v[134:135], v[6:7], v[154:155]
	v_pk_fma_f32 v[36:37], v[136:137], v[8:9], v[156:157]
	v_pk_fma_f32 v[30:31], v[142:143], v[14:15], v[30:31]
	v_pk_fma_f32 v[32:33], v[144:145], v[16:17], v[32:33]
	v_pk_fma_f32 v[34:35], v[130:131], v[2:3], v[34:35]
	v_pk_fma_f32 v[36:37], v[132:133], v[4:5], v[36:37]
	v_pk_fma_f32 v[30:31], v[150:151], v[22:23], v[30:31]
	v_pk_fma_f32 v[32:33], v[152:153], v[24:25], v[32:33]
	v_pk_fma_f32 v[34:35], v[138:139], v[10:11], v[34:35]
	v_pk_fma_f32 v[36:37], v[140:141], v[12:13], v[36:37]
	v_mul_f32_e32 v42, 0xbfb8aa3b, v30
	v_mul_f32_e32 v43, 0xbfb8aa3b, v31
	v_mul_f32_e32 v44, 0xbfb8aa3b, v32
	v_mul_f32_e32 v45, 0xbfb8aa3b, v33
	v_exp_f32_e32 v42, v42
	v_exp_f32_e32 v43, v43
	v_exp_f32_e32 v44, v44
	v_exp_f32_e32 v45, v45
	v_pk_add_f32 v[42:43], v[42:43], 1.0 op_sel_hi:[1,0]
	v_pk_add_f32 v[44:45], v[44:45], 1.0 op_sel_hi:[1,0]
	v_rcp_f32_e32 v46, v42
	v_rcp_f32_e32 v47, v43
	v_rcp_f32_e32 v48, v44
	v_rcp_f32_e32 v49, v45
	v_mul_f32_e32 v46, v30, v46
	v_mul_f32_e32 v47, v31, v47
	v_mul_f32_e32 v48, v32, v48
	v_mul_f32_e32 v49, v33, v49
	v_pk_mul_f32 v[34:35], v[34:35], v[46:47]
	v_pk_mul_f32 v[36:37], v[36:37], v[48:49]
	v_cvt_pk_bf16_f32 v66, v34, v35
	v_cvt_pk_bf16_f32 v67, v36, v37
	global_store_dwordx2 v[58:59], v[66:67], off
	v_lshl_add_u64 v[58:59], v[58:59], 0, v[56:57]
	s_waitcnt lgkmcnt(0)
	v_lshlrev_b32_e32 v2, 16, v26
	v_and_b32_e32 v3, 0xffff0000, v26
	v_lshlrev_b32_e32 v4, 16, v27
	v_and_b32_e32 v5, 0xffff0000, v27
	v_lshlrev_b32_e32 v14, 16, v28
	v_and_b32_e32 v15, 0xffff0000, v28
	v_lshlrev_b32_e32 v16, 16, v29
	v_and_b32_e32 v17, 0xffff0000, v29
	v_add_u32_e32 v63, 0x210, v63
	ds_read2_b64 v[26:29], v63 offset1:32
	v_pk_fma_f32 v[30:31], v[146:147], v[22:23], v[158:159]
	v_pk_fma_f32 v[32:33], v[148:149], v[24:25], v[160:161]
	v_pk_fma_f32 v[34:35], v[134:135], v[10:11], v[154:155]
	v_pk_fma_f32 v[36:37], v[136:137], v[12:13], v[156:157]
	v_pk_fma_f32 v[30:31], v[142:143], v[18:19], v[30:31]
	v_pk_fma_f32 v[32:33], v[144:145], v[20:21], v[32:33]
	v_pk_fma_f32 v[34:35], v[130:131], v[6:7], v[34:35]
	v_pk_fma_f32 v[36:37], v[132:133], v[8:9], v[36:37]
	v_pk_fma_f32 v[30:31], v[150:151], v[14:15], v[30:31]
	v_pk_fma_f32 v[32:33], v[152:153], v[16:17], v[32:33]
	v_pk_fma_f32 v[34:35], v[138:139], v[2:3], v[34:35]
	v_pk_fma_f32 v[36:37], v[140:141], v[4:5], v[36:37]
	v_mul_f32_e32 v42, 0xbfb8aa3b, v30
	v_mul_f32_e32 v43, 0xbfb8aa3b, v31
	v_mul_f32_e32 v44, 0xbfb8aa3b, v32
	v_mul_f32_e32 v45, 0xbfb8aa3b, v33
	v_exp_f32_e32 v42, v42
	v_exp_f32_e32 v43, v43
	v_exp_f32_e32 v44, v44
	v_exp_f32_e32 v45, v45
	v_pk_add_f32 v[42:43], v[42:43], 1.0 op_sel_hi:[1,0]
	v_pk_add_f32 v[44:45], v[44:45], 1.0 op_sel_hi:[1,0]
	v_rcp_f32_e32 v46, v42
	v_rcp_f32_e32 v47, v43
	v_rcp_f32_e32 v48, v44
	v_rcp_f32_e32 v49, v45
	v_mul_f32_e32 v46, v30, v46
	v_mul_f32_e32 v47, v31, v47
	v_mul_f32_e32 v48, v32, v48
	v_mul_f32_e32 v49, v33, v49
	v_pk_mul_f32 v[34:35], v[34:35], v[46:47]
	v_pk_mul_f32 v[36:37], v[36:37], v[48:49]
	v_cvt_pk_bf16_f32 v66, v34, v35
	v_cvt_pk_bf16_f32 v67, v36, v37
	global_store_dwordx2 v[58:59], v[66:67], off
	v_lshl_add_u64 v[58:59], v[58:59], 0, v[56:57]
	s_waitcnt lgkmcnt(0)
	v_lshlrev_b32_e32 v6, 16, v26
	v_and_b32_e32 v7, 0xffff0000, v26
	v_lshlrev_b32_e32 v8, 16, v27
	v_and_b32_e32 v9, 0xffff0000, v27
	v_lshlrev_b32_e32 v18, 16, v28
	v_and_b32_e32 v19, 0xffff0000, v28
	v_lshlrev_b32_e32 v20, 16, v29
	v_and_b32_e32 v21, 0xffff0000, v29
	v_add_u32_e32 v63, 0x210, v63
	ds_read2_b64 v[26:29], v63 offset1:32
	v_pk_fma_f32 v[30:31], v[146:147], v[14:15], v[158:159]
	v_pk_fma_f32 v[32:33], v[148:149], v[16:17], v[160:161]
	v_pk_fma_f32 v[34:35], v[134:135], v[2:3], v[154:155]
	v_pk_fma_f32 v[36:37], v[136:137], v[4:5], v[156:157]
	v_pk_fma_f32 v[30:31], v[142:143], v[22:23], v[30:31]
	v_pk_fma_f32 v[32:33], v[144:145], v[24:25], v[32:33]
	v_pk_fma_f32 v[34:35], v[130:131], v[10:11], v[34:35]
	v_pk_fma_f32 v[36:37], v[132:133], v[12:13], v[36:37]
	v_pk_fma_f32 v[30:31], v[150:151], v[18:19], v[30:31]
	v_pk_fma_f32 v[32:33], v[152:153], v[20:21], v[32:33]
	v_pk_fma_f32 v[34:35], v[138:139], v[6:7], v[34:35]
	v_pk_fma_f32 v[36:37], v[140:141], v[8:9], v[36:37]
	v_mul_f32_e32 v42, 0xbfb8aa3b, v30
	v_mul_f32_e32 v43, 0xbfb8aa3b, v31
	v_mul_f32_e32 v44, 0xbfb8aa3b, v32
	v_mul_f32_e32 v45, 0xbfb8aa3b, v33
	v_exp_f32_e32 v42, v42
	v_exp_f32_e32 v43, v43
	v_exp_f32_e32 v44, v44
	v_exp_f32_e32 v45, v45
	v_pk_add_f32 v[42:43], v[42:43], 1.0 op_sel_hi:[1,0]
	v_pk_add_f32 v[44:45], v[44:45], 1.0 op_sel_hi:[1,0]
	v_rcp_f32_e32 v46, v42
	v_rcp_f32_e32 v47, v43
	v_rcp_f32_e32 v48, v44
	v_rcp_f32_e32 v49, v45
	v_mul_f32_e32 v46, v30, v46
	v_mul_f32_e32 v47, v31, v47
	v_mul_f32_e32 v48, v32, v48
	v_mul_f32_e32 v49, v33, v49
	v_pk_mul_f32 v[34:35], v[34:35], v[46:47]
	v_pk_mul_f32 v[36:37], v[36:37], v[48:49]
	v_cvt_pk_bf16_f32 v66, v34, v35
	v_cvt_pk_bf16_f32 v67, v36, v37
	global_store_dwordx2 v[58:59], v[66:67], off
	v_lshl_add_u64 v[58:59], v[58:59], 0, v[56:57]
	s_waitcnt lgkmcnt(0)
	v_lshlrev_b32_e32 v10, 16, v26
	v_and_b32_e32 v11, 0xffff0000, v26
	v_lshlrev_b32_e32 v12, 16, v27
	v_and_b32_e32 v13, 0xffff0000, v27
	v_lshlrev_b32_e32 v22, 16, v28
	v_and_b32_e32 v23, 0xffff0000, v28
	v_lshlrev_b32_e32 v24, 16, v29
	v_and_b32_e32 v25, 0xffff0000, v29
	v_add_u32_e32 v63, 0x210, v63
	ds_read2_b64 v[26:29], v63 offset1:32
	v_pk_fma_f32 v[30:31], v[146:147], v[18:19], v[158:159]
	v_pk_fma_f32 v[32:33], v[148:149], v[20:21], v[160:161]
	v_pk_fma_f32 v[34:35], v[134:135], v[6:7], v[154:155]
	v_pk_fma_f32 v[36:37], v[136:137], v[8:9], v[156:157]
	v_pk_fma_f32 v[30:31], v[142:143], v[14:15], v[30:31]
	v_pk_fma_f32 v[32:33], v[144:145], v[16:17], v[32:33]
	v_pk_fma_f32 v[34:35], v[130:131], v[2:3], v[34:35]
	v_pk_fma_f32 v[36:37], v[132:133], v[4:5], v[36:37]
	v_pk_fma_f32 v[30:31], v[150:151], v[22:23], v[30:31]
	v_pk_fma_f32 v[32:33], v[152:153], v[24:25], v[32:33]
	v_pk_fma_f32 v[34:35], v[138:139], v[10:11], v[34:35]
	v_pk_fma_f32 v[36:37], v[140:141], v[12:13], v[36:37]
	v_mul_f32_e32 v42, 0xbfb8aa3b, v30
	v_mul_f32_e32 v43, 0xbfb8aa3b, v31
	v_mul_f32_e32 v44, 0xbfb8aa3b, v32
	v_mul_f32_e32 v45, 0xbfb8aa3b, v33
	v_exp_f32_e32 v42, v42
	v_exp_f32_e32 v43, v43
	v_exp_f32_e32 v44, v44
	v_exp_f32_e32 v45, v45
	v_pk_add_f32 v[42:43], v[42:43], 1.0 op_sel_hi:[1,0]
	v_pk_add_f32 v[44:45], v[44:45], 1.0 op_sel_hi:[1,0]
	v_rcp_f32_e32 v46, v42
	v_rcp_f32_e32 v47, v43
	v_rcp_f32_e32 v48, v44
	v_rcp_f32_e32 v49, v45
	v_mul_f32_e32 v46, v30, v46
	v_mul_f32_e32 v47, v31, v47
	v_mul_f32_e32 v48, v32, v48
	v_mul_f32_e32 v49, v33, v49
	v_pk_mul_f32 v[34:35], v[34:35], v[46:47]
	v_pk_mul_f32 v[36:37], v[36:37], v[48:49]
	v_cvt_pk_bf16_f32 v66, v34, v35
	v_cvt_pk_bf16_f32 v67, v36, v37
	global_store_dwordx2 v[58:59], v[66:67], off
	v_lshl_add_u64 v[58:59], v[58:59], 0, v[56:57]
	s_waitcnt lgkmcnt(0)
	v_lshlrev_b32_e32 v2, 16, v26
	v_and_b32_e32 v3, 0xffff0000, v26
	v_lshlrev_b32_e32 v4, 16, v27
	v_and_b32_e32 v5, 0xffff0000, v27
	v_lshlrev_b32_e32 v14, 16, v28
	v_and_b32_e32 v15, 0xffff0000, v28
	v_lshlrev_b32_e32 v16, 16, v29
	v_and_b32_e32 v17, 0xffff0000, v29
	v_add_u32_e32 v63, 0x210, v63
	ds_read2_b64 v[26:29], v63 offset1:32
	v_pk_fma_f32 v[30:31], v[146:147], v[22:23], v[158:159]
	v_pk_fma_f32 v[32:33], v[148:149], v[24:25], v[160:161]
	v_pk_fma_f32 v[34:35], v[134:135], v[10:11], v[154:155]
	v_pk_fma_f32 v[36:37], v[136:137], v[12:13], v[156:157]
	v_pk_fma_f32 v[30:31], v[142:143], v[18:19], v[30:31]
	v_pk_fma_f32 v[32:33], v[144:145], v[20:21], v[32:33]
	v_pk_fma_f32 v[34:35], v[130:131], v[6:7], v[34:35]
	v_pk_fma_f32 v[36:37], v[132:133], v[8:9], v[36:37]
	v_pk_fma_f32 v[30:31], v[150:151], v[14:15], v[30:31]
	v_pk_fma_f32 v[32:33], v[152:153], v[16:17], v[32:33]
	v_pk_fma_f32 v[34:35], v[138:139], v[2:3], v[34:35]
	v_pk_fma_f32 v[36:37], v[140:141], v[4:5], v[36:37]
	v_mul_f32_e32 v42, 0xbfb8aa3b, v30
	v_mul_f32_e32 v43, 0xbfb8aa3b, v31
	v_mul_f32_e32 v44, 0xbfb8aa3b, v32
	v_mul_f32_e32 v45, 0xbfb8aa3b, v33
	v_exp_f32_e32 v42, v42
	v_exp_f32_e32 v43, v43
	v_exp_f32_e32 v44, v44
	v_exp_f32_e32 v45, v45
	v_pk_add_f32 v[42:43], v[42:43], 1.0 op_sel_hi:[1,0]
	v_pk_add_f32 v[44:45], v[44:45], 1.0 op_sel_hi:[1,0]
	v_rcp_f32_e32 v46, v42
	v_rcp_f32_e32 v47, v43
	v_rcp_f32_e32 v48, v44
	v_rcp_f32_e32 v49, v45
	v_mul_f32_e32 v46, v30, v46
	v_mul_f32_e32 v47, v31, v47
	v_mul_f32_e32 v48, v32, v48
	v_mul_f32_e32 v49, v33, v49
	v_pk_mul_f32 v[34:35], v[34:35], v[46:47]
	v_pk_mul_f32 v[36:37], v[36:37], v[48:49]
	v_cvt_pk_bf16_f32 v66, v34, v35
	v_cvt_pk_bf16_f32 v67, v36, v37
	global_store_dwordx2 v[58:59], v[66:67], off
	v_lshl_add_u64 v[58:59], v[58:59], 0, v[56:57]
	s_waitcnt lgkmcnt(0)
	v_lshlrev_b32_e32 v6, 16, v26
	v_and_b32_e32 v7, 0xffff0000, v26
	v_lshlrev_b32_e32 v8, 16, v27
	v_and_b32_e32 v9, 0xffff0000, v27
	v_lshlrev_b32_e32 v18, 16, v28
	v_and_b32_e32 v19, 0xffff0000, v28
	v_lshlrev_b32_e32 v20, 16, v29
	v_and_b32_e32 v21, 0xffff0000, v29
	v_add_u32_e32 v63, 0x210, v63
	ds_read2_b64 v[26:29], v63 offset1:32
	v_pk_fma_f32 v[30:31], v[146:147], v[14:15], v[158:159]
	v_pk_fma_f32 v[32:33], v[148:149], v[16:17], v[160:161]
	v_pk_fma_f32 v[34:35], v[134:135], v[2:3], v[154:155]
	v_pk_fma_f32 v[36:37], v[136:137], v[4:5], v[156:157]
	v_pk_fma_f32 v[30:31], v[142:143], v[22:23], v[30:31]
	v_pk_fma_f32 v[32:33], v[144:145], v[24:25], v[32:33]
	v_pk_fma_f32 v[34:35], v[130:131], v[10:11], v[34:35]
	v_pk_fma_f32 v[36:37], v[132:133], v[12:13], v[36:37]
	v_pk_fma_f32 v[30:31], v[150:151], v[18:19], v[30:31]
	v_pk_fma_f32 v[32:33], v[152:153], v[20:21], v[32:33]
	v_pk_fma_f32 v[34:35], v[138:139], v[6:7], v[34:35]
	v_pk_fma_f32 v[36:37], v[140:141], v[8:9], v[36:37]
	v_mul_f32_e32 v42, 0xbfb8aa3b, v30
	v_mul_f32_e32 v43, 0xbfb8aa3b, v31
	v_mul_f32_e32 v44, 0xbfb8aa3b, v32
	v_mul_f32_e32 v45, 0xbfb8aa3b, v33
	v_exp_f32_e32 v42, v42
	v_exp_f32_e32 v43, v43
	v_exp_f32_e32 v44, v44
	v_exp_f32_e32 v45, v45
	v_pk_add_f32 v[42:43], v[42:43], 1.0 op_sel_hi:[1,0]
	v_pk_add_f32 v[44:45], v[44:45], 1.0 op_sel_hi:[1,0]
	v_rcp_f32_e32 v46, v42
	v_rcp_f32_e32 v47, v43
	v_rcp_f32_e32 v48, v44
	v_rcp_f32_e32 v49, v45
	v_mul_f32_e32 v46, v30, v46
	v_mul_f32_e32 v47, v31, v47
	v_mul_f32_e32 v48, v32, v48
	v_mul_f32_e32 v49, v33, v49
	v_pk_mul_f32 v[34:35], v[34:35], v[46:47]
	v_pk_mul_f32 v[36:37], v[36:37], v[48:49]
	v_cvt_pk_bf16_f32 v66, v34, v35
	v_cvt_pk_bf16_f32 v67, v36, v37
	global_store_dwordx2 v[58:59], v[66:67], off
	v_lshl_add_u64 v[58:59], v[58:59], 0, v[56:57]
	s_waitcnt lgkmcnt(0)
	v_lshlrev_b32_e32 v10, 16, v26
	v_and_b32_e32 v11, 0xffff0000, v26
	v_lshlrev_b32_e32 v12, 16, v27
	v_and_b32_e32 v13, 0xffff0000, v27
	v_lshlrev_b32_e32 v22, 16, v28
	v_and_b32_e32 v23, 0xffff0000, v28
	v_lshlrev_b32_e32 v24, 16, v29
	v_and_b32_e32 v25, 0xffff0000, v29
	v_pk_fma_f32 v[30:31], v[146:147], v[18:19], v[158:159]
	v_pk_fma_f32 v[32:33], v[148:149], v[20:21], v[160:161]
	v_pk_fma_f32 v[34:35], v[134:135], v[6:7], v[154:155]
	v_pk_fma_f32 v[36:37], v[136:137], v[8:9], v[156:157]
	v_pk_fma_f32 v[30:31], v[142:143], v[14:15], v[30:31]
	v_pk_fma_f32 v[32:33], v[144:145], v[16:17], v[32:33]
	v_pk_fma_f32 v[34:35], v[130:131], v[2:3], v[34:35]
	v_pk_fma_f32 v[36:37], v[132:133], v[4:5], v[36:37]
	v_pk_fma_f32 v[30:31], v[150:151], v[22:23], v[30:31]
	v_pk_fma_f32 v[32:33], v[152:153], v[24:25], v[32:33]
	v_pk_fma_f32 v[34:35], v[138:139], v[10:11], v[34:35]
	v_pk_fma_f32 v[36:37], v[140:141], v[12:13], v[36:37]
	v_mul_f32_e32 v42, 0xbfb8aa3b, v30
	v_mul_f32_e32 v43, 0xbfb8aa3b, v31
	v_mul_f32_e32 v44, 0xbfb8aa3b, v32
	v_mul_f32_e32 v45, 0xbfb8aa3b, v33
	v_exp_f32_e32 v42, v42
	v_exp_f32_e32 v43, v43
	v_exp_f32_e32 v44, v44
	v_exp_f32_e32 v45, v45
	v_pk_add_f32 v[42:43], v[42:43], 1.0 op_sel_hi:[1,0]
	v_pk_add_f32 v[44:45], v[44:45], 1.0 op_sel_hi:[1,0]
	v_rcp_f32_e32 v46, v42
	v_rcp_f32_e32 v47, v43
	v_rcp_f32_e32 v48, v44
	v_rcp_f32_e32 v49, v45
	v_mul_f32_e32 v46, v30, v46
	v_mul_f32_e32 v47, v31, v47
	v_mul_f32_e32 v48, v32, v48
	v_mul_f32_e32 v49, v33, v49
	v_pk_mul_f32 v[34:35], v[34:35], v[46:47]
	v_pk_mul_f32 v[36:37], v[36:37], v[48:49]
	v_cvt_pk_bf16_f32 v66, v34, v35
	v_cvt_pk_bf16_f32 v67, v36, v37
	global_store_dwordx2 v[58:59], v[66:67], off
	v_lshl_add_u64 v[58:59], v[58:59], 0, v[56:57]
	s_branch .Lconv_done
.Lconv_slow:
	ds_read2_b64 v[26:29], v63 offset1:32
	v_and_b32_e32 v64, 0xfffffeff, v60
	v_and_b32_e32 v65, 0xffffefff, v60
	v_cmp_eq_u32_e32 vcc, 0, v64
	v_cmp_eq_u32_e64 s[2:3], s33, v65
	v_add_u32_e32 v63, 0x210, v63
	s_nop 0
	v_cndmask_b32_e64 v52, 1.0, 0, vcc
	v_cndmask_b32_e64 v54, 1.0, 0, s[2:3]
	s_waitcnt lgkmcnt(0)
	v_lshlrev_b32_e32 v10, 16, v26
	v_and_b32_e32 v11, 0xffff0000, v26
	v_lshlrev_b32_e32 v12, 16, v27
	v_and_b32_e32 v13, 0xffff0000, v27
	v_lshlrev_b32_e32 v22, 16, v28
	v_and_b32_e32 v23, 0xffff0000, v28
	v_lshlrev_b32_e32 v24, 16, v29
	v_and_b32_e32 v25, 0xffff0000, v29
	v_pk_fma_f32 v[30:31], v[146:147], v[18:19], v[158:159]
	v_pk_fma_f32 v[32:33], v[148:149], v[20:21], v[160:161]
	v_pk_mul_f32 v[38:39], v[52:53], v[14:15] op_sel_hi:[0,1]
	v_pk_mul_f32 v[40:41], v[52:53], v[16:17] op_sel_hi:[0,1]
	v_pk_fma_f32 v[30:31], v[142:143], v[38:39], v[30:31]
	v_pk_fma_f32 v[32:33], v[144:145], v[40:41], v[32:33]
	v_pk_mul_f32 v[38:39], v[54:55], v[22:23] op_sel_hi:[0,1]
	v_pk_mul_f32 v[40:41], v[54:55], v[24:25] op_sel_hi:[0,1]
	v_pk_fma_f32 v[30:31], v[150:151], v[38:39], v[30:31]
	v_pk_fma_f32 v[32:33], v[152:153], v[40:41], v[32:33]
	v_pk_fma_f32 v[34:35], v[134:135], v[6:7], v[154:155]
	v_pk_fma_f32 v[36:37], v[136:137], v[8:9], v[156:157]
	v_pk_mul_f32 v[38:39], v[52:53], v[2:3] op_sel_hi:[0,1]
	v_pk_mul_f32 v[40:41], v[52:53], v[4:5] op_sel_hi:[0,1]
	v_pk_fma_f32 v[34:35], v[130:131], v[38:39], v[34:35]
	v_pk_fma_f32 v[36:37], v[132:133], v[40:41], v[36:37]
	v_pk_mul_f32 v[38:39], v[54:55], v[10:11] op_sel_hi:[0,1]
	v_pk_mul_f32 v[40:41], v[54:55], v[12:13] op_sel_hi:[0,1]
	v_pk_fma_f32 v[34:35], v[138:139], v[38:39], v[34:35]
	v_pk_fma_f32 v[36:37], v[140:141], v[40:41], v[36:37]
	v_mul_f32_e32 v42, 0xbfb8aa3b, v30
	v_exp_f32_e32 v42, v42
	v_mul_f32_e32 v43, 0xbfb8aa3b, v31
	v_exp_f32_e32 v43, v43
	v_mul_f32_e32 v44, 0xbfb8aa3b, v32
	v_exp_f32_e32 v44, v44
	v_mul_f32_e32 v45, 0xbfb8aa3b, v33
	v_exp_f32_e32 v45, v45
	v_pk_add_f32 v[42:43], v[42:43], 1.0 op_sel_hi:[1,0]
	v_pk_add_f32 v[44:45], v[44:45], 1.0 op_sel_hi:[1,0]
	v_rcp_f32_e32 v46, v42
	v_rcp_f32_e32 v47, v43
	v_rcp_f32_e32 v48, v44
	v_rcp_f32_e32 v49, v45
	v_mul_f32_e32 v46, v30, v46
	v_mul_f32_e32 v47, v31, v47
	v_mul_f32_e32 v48, v32, v48
	v_mul_f32_e32 v49, v33, v49
	v_pk_mul_f32 v[34:35], v[34:35], v[46:47]
	v_pk_mul_f32 v[36:37], v[36:37], v[48:49]
	v_cvt_pk_bf16_f32 v66, v34, v35
	v_cvt_pk_bf16_f32 v67, v36, v37
	v_cmp_gt_i32_e32 vcc, s33, v61
	v_cmp_gt_i32_e64 s[2:3], s14, v62
	v_add_u32_e32 v61, 1, v61
	v_add_u32_e32 v62, 1, v62
	s_and_b64 s[2:3], vcc, s[2:3]
	s_and_saveexec_b64 s[4:5], s[2:3]
	global_store_dwordx2 v[58:59], v[66:67], off
	s_or_b64 exec, exec, s[4:5]
	v_add_u32_e32 v60, 1, v60
	v_lshl_add_u64 v[58:59], v[58:59], 0, v[56:57]
	v_cmp_ne_u32_e32 vcc, 0x1100, v60
	s_nop 1
	v_cndmask_b32_e32 v60, 0, v60, vcc
	ds_read2_b64 v[26:29], v63 offset1:32
	v_and_b32_e32 v64, 0xfffffeff, v60
	v_and_b32_e32 v65, 0xffffefff, v60
	v_cmp_eq_u32_e32 vcc, 0, v64
	v_cmp_eq_u32_e64 s[2:3], s33, v65
	v_add_u32_e32 v63, 0x210, v63
	s_nop 0
	v_cndmask_b32_e64 v52, 1.0, 0, vcc
	v_cndmask_b32_e64 v54, 1.0, 0, s[2:3]
	s_waitcnt lgkmcnt(0)
	v_lshlrev_b32_e32 v2, 16, v26
	v_and_b32_e32 v3, 0xffff0000, v26
	v_lshlrev_b32_e32 v4, 16, v27
	v_and_b32_e32 v5, 0xffff0000, v27
	v_lshlrev_b32_e32 v14, 16, v28
	v_and_b32_e32 v15, 0xffff0000, v28
	v_lshlrev_b32_e32 v16, 16, v29
	v_and_b32_e32 v17, 0xffff0000, v29
	v_pk_fma_f32 v[30:31], v[146:147], v[22:23], v[158:159]
	v_pk_fma_f32 v[32:33], v[148:149], v[24:25], v[160:161]
	v_pk_mul_f32 v[38:39], v[52:53], v[18:19] op_sel_hi:[0,1]
	v_pk_mul_f32 v[40:41], v[52:53], v[20:21] op_sel_hi:[0,1]
	v_pk_fma_f32 v[30:31], v[142:143], v[38:39], v[30:31]
	v_pk_fma_f32 v[32:33], v[144:145], v[40:41], v[32:33]
	v_pk_mul_f32 v[38:39], v[54:55], v[14:15] op_sel_hi:[0,1]
	v_pk_mul_f32 v[40:41], v[54:55], v[16:17] op_sel_hi:[0,1]
	v_pk_fma_f32 v[30:31], v[150:151], v[38:39], v[30:31]
	v_pk_fma_f32 v[32:33], v[152:153], v[40:41], v[32:33]
	v_pk_fma_f32 v[34:35], v[134:135], v[10:11], v[154:155]
	v_pk_fma_f32 v[36:37], v[136:137], v[12:13], v[156:157]
	v_pk_mul_f32 v[38:39], v[52:53], v[6:7] op_sel_hi:[0,1]
	v_pk_mul_f32 v[40:41], v[52:53], v[8:9] op_sel_hi:[0,1]
	v_pk_fma_f32 v[34:35], v[130:131], v[38:39], v[34:35]
	v_pk_fma_f32 v[36:37], v[132:133], v[40:41], v[36:37]
	v_pk_mul_f32 v[38:39], v[54:55], v[2:3] op_sel_hi:[0,1]
	v_pk_mul_f32 v[40:41], v[54:55], v[4:5] op_sel_hi:[0,1]
	v_pk_fma_f32 v[34:35], v[138:139], v[38:39], v[34:35]
	v_pk_fma_f32 v[36:37], v[140:141], v[40:41], v[36:37]
	v_mul_f32_e32 v42, 0xbfb8aa3b, v30
	v_exp_f32_e32 v42, v42
	v_mul_f32_e32 v43, 0xbfb8aa3b, v31
	v_exp_f32_e32 v43, v43
	v_mul_f32_e32 v44, 0xbfb8aa3b, v32
	v_exp_f32_e32 v44, v44
	v_mul_f32_e32 v45, 0xbfb8aa3b, v33
	v_exp_f32_e32 v45, v45
	v_pk_add_f32 v[42:43], v[42:43], 1.0 op_sel_hi:[1,0]
	v_pk_add_f32 v[44:45], v[44:45], 1.0 op_sel_hi:[1,0]
	v_rcp_f32_e32 v46, v42
	v_rcp_f32_e32 v47, v43
	v_rcp_f32_e32 v48, v44
	v_rcp_f32_e32 v49, v45
	v_mul_f32_e32 v46, v30, v46
	v_mul_f32_e32 v47, v31, v47
	v_mul_f32_e32 v48, v32, v48
	v_mul_f32_e32 v49, v33, v49
	v_pk_mul_f32 v[34:35], v[34:35], v[46:47]
	v_pk_mul_f32 v[36:37], v[36:37], v[48:49]
	v_cvt_pk_bf16_f32 v66, v34, v35
	v_cvt_pk_bf16_f32 v67, v36, v37
	v_cmp_gt_i32_e32 vcc, s33, v61
	v_cmp_gt_i32_e64 s[2:3], s14, v62
	v_add_u32_e32 v61, 1, v61
	v_add_u32_e32 v62, 1, v62
	s_and_b64 s[2:3], vcc, s[2:3]
	s_and_saveexec_b64 s[4:5], s[2:3]
	global_store_dwordx2 v[58:59], v[66:67], off
	s_or_b64 exec, exec, s[4:5]
	v_add_u32_e32 v60, 1, v60
	v_lshl_add_u64 v[58:59], v[58:59], 0, v[56:57]
	v_cmp_ne_u32_e32 vcc, 0x1100, v60
	s_nop 1
	v_cndmask_b32_e32 v60, 0, v60, vcc
	ds_read2_b64 v[26:29], v63 offset1:32
	v_and_b32_e32 v64, 0xfffffeff, v60
	v_and_b32_e32 v65, 0xffffefff, v60
	v_cmp_eq_u32_e32 vcc, 0, v64
	v_cmp_eq_u32_e64 s[2:3], s33, v65
	v_add_u32_e32 v63, 0x210, v63
	s_nop 0
	v_cndmask_b32_e64 v52, 1.0, 0, vcc
	v_cndmask_b32_e64 v54, 1.0, 0, s[2:3]
	s_waitcnt lgkmcnt(0)
	v_lshlrev_b32_e32 v6, 16, v26
	v_and_b32_e32 v7, 0xffff0000, v26
	v_lshlrev_b32_e32 v8, 16, v27
	v_and_b32_e32 v9, 0xffff0000, v27
	v_lshlrev_b32_e32 v18, 16, v28
	v_and_b32_e32 v19, 0xffff0000, v28
	v_lshlrev_b32_e32 v20, 16, v29
	v_and_b32_e32 v21, 0xffff0000, v29
	v_pk_fma_f32 v[30:31], v[146:147], v[14:15], v[158:159]
	v_pk_fma_f32 v[32:33], v[148:149], v[16:17], v[160:161]
	v_pk_mul_f32 v[38:39], v[52:53], v[22:23] op_sel_hi:[0,1]
	v_pk_mul_f32 v[40:41], v[52:53], v[24:25] op_sel_hi:[0,1]
	v_pk_fma_f32 v[30:31], v[142:143], v[38:39], v[30:31]
	v_pk_fma_f32 v[32:33], v[144:145], v[40:41], v[32:33]
	v_pk_mul_f32 v[38:39], v[54:55], v[18:19] op_sel_hi:[0,1]
	v_pk_mul_f32 v[40:41], v[54:55], v[20:21] op_sel_hi:[0,1]
	v_pk_fma_f32 v[30:31], v[150:151], v[38:39], v[30:31]
	v_pk_fma_f32 v[32:33], v[152:153], v[40:41], v[32:33]
	v_pk_fma_f32 v[34:35], v[134:135], v[2:3], v[154:155]
	v_pk_fma_f32 v[36:37], v[136:137], v[4:5], v[156:157]
	v_pk_mul_f32 v[38:39], v[52:53], v[10:11] op_sel_hi:[0,1]
	v_pk_mul_f32 v[40:41], v[52:53], v[12:13] op_sel_hi:[0,1]
	v_pk_fma_f32 v[34:35], v[130:131], v[38:39], v[34:35]
	v_pk_fma_f32 v[36:37], v[132:133], v[40:41], v[36:37]
	v_pk_mul_f32 v[38:39], v[54:55], v[6:7] op_sel_hi:[0,1]
	v_pk_mul_f32 v[40:41], v[54:55], v[8:9] op_sel_hi:[0,1]
	v_pk_fma_f32 v[34:35], v[138:139], v[38:39], v[34:35]
	v_pk_fma_f32 v[36:37], v[140:141], v[40:41], v[36:37]
	v_mul_f32_e32 v42, 0xbfb8aa3b, v30
	v_exp_f32_e32 v42, v42
	v_mul_f32_e32 v43, 0xbfb8aa3b, v31
	v_exp_f32_e32 v43, v43
	v_mul_f32_e32 v44, 0xbfb8aa3b, v32
	v_exp_f32_e32 v44, v44
	v_mul_f32_e32 v45, 0xbfb8aa3b, v33
	v_exp_f32_e32 v45, v45
	v_pk_add_f32 v[42:43], v[42:43], 1.0 op_sel_hi:[1,0]
	v_pk_add_f32 v[44:45], v[44:45], 1.0 op_sel_hi:[1,0]
	v_rcp_f32_e32 v46, v42
	v_rcp_f32_e32 v47, v43
	v_rcp_f32_e32 v48, v44
	v_rcp_f32_e32 v49, v45
	v_mul_f32_e32 v46, v30, v46
	v_mul_f32_e32 v47, v31, v47
	v_mul_f32_e32 v48, v32, v48
	v_mul_f32_e32 v49, v33, v49
	v_pk_mul_f32 v[34:35], v[34:35], v[46:47]
	v_pk_mul_f32 v[36:37], v[36:37], v[48:49]
	v_cvt_pk_bf16_f32 v66, v34, v35
	v_cvt_pk_bf16_f32 v67, v36, v37
	v_cmp_gt_i32_e32 vcc, s33, v61
	v_cmp_gt_i32_e64 s[2:3], s14, v62
	v_add_u32_e32 v61, 1, v61
	v_add_u32_e32 v62, 1, v62
	s_and_b64 s[2:3], vcc, s[2:3]
	s_and_saveexec_b64 s[4:5], s[2:3]
	global_store_dwordx2 v[58:59], v[66:67], off
	s_or_b64 exec, exec, s[4:5]
	v_add_u32_e32 v60, 1, v60
	v_lshl_add_u64 v[58:59], v[58:59], 0, v[56:57]
	v_cmp_ne_u32_e32 vcc, 0x1100, v60
	s_nop 1
	v_cndmask_b32_e32 v60, 0, v60, vcc
	ds_read2_b64 v[26:29], v63 offset1:32
	v_and_b32_e32 v64, 0xfffffeff, v60
	v_and_b32_e32 v65, 0xffffefff, v60
	v_cmp_eq_u32_e32 vcc, 0, v64
	v_cmp_eq_u32_e64 s[2:3], s33, v65
	v_add_u32_e32 v63, 0x210, v63
	s_nop 0
	v_cndmask_b32_e64 v52, 1.0, 0, vcc
	v_cndmask_b32_e64 v54, 1.0, 0, s[2:3]
	s_waitcnt lgkmcnt(0)
	v_lshlrev_b32_e32 v10, 16, v26
	v_and_b32_e32 v11, 0xffff0000, v26
	v_lshlrev_b32_e32 v12, 16, v27
	v_and_b32_e32 v13, 0xffff0000, v27
	v_lshlrev_b32_e32 v22, 16, v28
	v_and_b32_e32 v23, 0xffff0000, v28
	v_lshlrev_b32_e32 v24, 16, v29
	v_and_b32_e32 v25, 0xffff0000, v29
	v_pk_fma_f32 v[30:31], v[146:147], v[18:19], v[158:159]
	v_pk_fma_f32 v[32:33], v[148:149], v[20:21], v[160:161]
	v_pk_mul_f32 v[38:39], v[52:53], v[14:15] op_sel_hi:[0,1]
	v_pk_mul_f32 v[40:41], v[52:53], v[16:17] op_sel_hi:[0,1]
	v_pk_fma_f32 v[30:31], v[142:143], v[38:39], v[30:31]
	v_pk_fma_f32 v[32:33], v[144:145], v[40:41], v[32:33]
	v_pk_mul_f32 v[38:39], v[54:55], v[22:23] op_sel_hi:[0,1]
	v_pk_mul_f32 v[40:41], v[54:55], v[24:25] op_sel_hi:[0,1]
	v_pk_fma_f32 v[30:31], v[150:151], v[38:39], v[30:31]
	v_pk_fma_f32 v[32:33], v[152:153], v[40:41], v[32:33]
	v_pk_fma_f32 v[34:35], v[134:135], v[6:7], v[154:155]
	v_pk_fma_f32 v[36:37], v[136:137], v[8:9], v[156:157]
	v_pk_mul_f32 v[38:39], v[52:53], v[2:3] op_sel_hi:[0,1]
	v_pk_mul_f32 v[40:41], v[52:53], v[4:5] op_sel_hi:[0,1]
	v_pk_fma_f32 v[34:35], v[130:131], v[38:39], v[34:35]
	v_pk_fma_f32 v[36:37], v[132:133], v[40:41], v[36:37]
	v_pk_mul_f32 v[38:39], v[54:55], v[10:11] op_sel_hi:[0,1]
	v_pk_mul_f32 v[40:41], v[54:55], v[12:13] op_sel_hi:[0,1]
	v_pk_fma_f32 v[34:35], v[138:139], v[38:39], v[34:35]
	v_pk_fma_f32 v[36:37], v[140:141], v[40:41], v[36:37]
	v_mul_f32_e32 v42, 0xbfb8aa3b, v30
	v_exp_f32_e32 v42, v42
	v_mul_f32_e32 v43, 0xbfb8aa3b, v31
	v_exp_f32_e32 v43, v43
	v_mul_f32_e32 v44, 0xbfb8aa3b, v32
	v_exp_f32_e32 v44, v44
	v_mul_f32_e32 v45, 0xbfb8aa3b, v33
	v_exp_f32_e32 v45, v45
	v_pk_add_f32 v[42:43], v[42:43], 1.0 op_sel_hi:[1,0]
	v_pk_add_f32 v[44:45], v[44:45], 1.0 op_sel_hi:[1,0]
	v_rcp_f32_e32 v46, v42
	v_rcp_f32_e32 v47, v43
	v_rcp_f32_e32 v48, v44
	v_rcp_f32_e32 v49, v45
	v_mul_f32_e32 v46, v30, v46
	v_mul_f32_e32 v47, v31, v47
	v_mul_f32_e32 v48, v32, v48
	v_mul_f32_e32 v49, v33, v49
	v_pk_mul_f32 v[34:35], v[34:35], v[46:47]
	v_pk_mul_f32 v[36:37], v[36:37], v[48:49]
	v_cvt_pk_bf16_f32 v66, v34, v35
	v_cvt_pk_bf16_f32 v67, v36, v37
	v_cmp_gt_i32_e32 vcc, s33, v61
	v_cmp_gt_i32_e64 s[2:3], s14, v62
	v_add_u32_e32 v61, 1, v61
	v_add_u32_e32 v62, 1, v62
	s_and_b64 s[2:3], vcc, s[2:3]
	s_and_saveexec_b64 s[4:5], s[2:3]
	global_store_dwordx2 v[58:59], v[66:67], off
	s_or_b64 exec, exec, s[4:5]
	v_add_u32_e32 v60, 1, v60
	v_lshl_add_u64 v[58:59], v[58:59], 0, v[56:57]
	v_cmp_ne_u32_e32 vcc, 0x1100, v60
	s_nop 1
	v_cndmask_b32_e32 v60, 0, v60, vcc
	ds_read2_b64 v[26:29], v63 offset1:32
	v_and_b32_e32 v64, 0xfffffeff, v60
	v_and_b32_e32 v65, 0xffffefff, v60
	v_cmp_eq_u32_e32 vcc, 0, v64
	v_cmp_eq_u32_e64 s[2:3], s33, v65
	v_add_u32_e32 v63, 0x210, v63
	s_nop 0
	v_cndmask_b32_e64 v52, 1.0, 0, vcc
	v_cndmask_b32_e64 v54, 1.0, 0, s[2:3]
	s_waitcnt lgkmcnt(0)
	v_lshlrev_b32_e32 v2, 16, v26
	v_and_b32_e32 v3, 0xffff0000, v26
	v_lshlrev_b32_e32 v4, 16, v27
	v_and_b32_e32 v5, 0xffff0000, v27
	v_lshlrev_b32_e32 v14, 16, v28
	v_and_b32_e32 v15, 0xffff0000, v28
	v_lshlrev_b32_e32 v16, 16, v29
	v_and_b32_e32 v17, 0xffff0000, v29
	v_pk_fma_f32 v[30:31], v[146:147], v[22:23], v[158:159]
	v_pk_fma_f32 v[32:33], v[148:149], v[24:25], v[160:161]
	v_pk_mul_f32 v[38:39], v[52:53], v[18:19] op_sel_hi:[0,1]
	v_pk_mul_f32 v[40:41], v[52:53], v[20:21] op_sel_hi:[0,1]
	v_pk_fma_f32 v[30:31], v[142:143], v[38:39], v[30:31]
	v_pk_fma_f32 v[32:33], v[144:145], v[40:41], v[32:33]
	v_pk_mul_f32 v[38:39], v[54:55], v[14:15] op_sel_hi:[0,1]
	v_pk_mul_f32 v[40:41], v[54:55], v[16:17] op_sel_hi:[0,1]
	v_pk_fma_f32 v[30:31], v[150:151], v[38:39], v[30:31]
	v_pk_fma_f32 v[32:33], v[152:153], v[40:41], v[32:33]
	v_pk_fma_f32 v[34:35], v[134:135], v[10:11], v[154:155]
	v_pk_fma_f32 v[36:37], v[136:137], v[12:13], v[156:157]
	v_pk_mul_f32 v[38:39], v[52:53], v[6:7] op_sel_hi:[0,1]
	v_pk_mul_f32 v[40:41], v[52:53], v[8:9] op_sel_hi:[0,1]
	v_pk_fma_f32 v[34:35], v[130:131], v[38:39], v[34:35]
	v_pk_fma_f32 v[36:37], v[132:133], v[40:41], v[36:37]
	v_pk_mul_f32 v[38:39], v[54:55], v[2:3] op_sel_hi:[0,1]
	v_pk_mul_f32 v[40:41], v[54:55], v[4:5] op_sel_hi:[0,1]
	v_pk_fma_f32 v[34:35], v[138:139], v[38:39], v[34:35]
	v_pk_fma_f32 v[36:37], v[140:141], v[40:41], v[36:37]
	v_mul_f32_e32 v42, 0xbfb8aa3b, v30
	v_exp_f32_e32 v42, v42
	v_mul_f32_e32 v43, 0xbfb8aa3b, v31
	v_exp_f32_e32 v43, v43
	v_mul_f32_e32 v44, 0xbfb8aa3b, v32
	v_exp_f32_e32 v44, v44
	v_mul_f32_e32 v45, 0xbfb8aa3b, v33
	v_exp_f32_e32 v45, v45
	v_pk_add_f32 v[42:43], v[42:43], 1.0 op_sel_hi:[1,0]
	v_pk_add_f32 v[44:45], v[44:45], 1.0 op_sel_hi:[1,0]
	v_rcp_f32_e32 v46, v42
	v_rcp_f32_e32 v47, v43
	v_rcp_f32_e32 v48, v44
	v_rcp_f32_e32 v49, v45
	v_mul_f32_e32 v46, v30, v46
	v_mul_f32_e32 v47, v31, v47
	v_mul_f32_e32 v48, v32, v48
	v_mul_f32_e32 v49, v33, v49
	v_pk_mul_f32 v[34:35], v[34:35], v[46:47]
	v_pk_mul_f32 v[36:37], v[36:37], v[48:49]
	v_cvt_pk_bf16_f32 v66, v34, v35
	v_cvt_pk_bf16_f32 v67, v36, v37
	v_cmp_gt_i32_e32 vcc, s33, v61
	v_cmp_gt_i32_e64 s[2:3], s14, v62
	v_add_u32_e32 v61, 1, v61
	v_add_u32_e32 v62, 1, v62
	s_and_b64 s[2:3], vcc, s[2:3]
	s_and_saveexec_b64 s[4:5], s[2:3]
	global_store_dwordx2 v[58:59], v[66:67], off
	s_or_b64 exec, exec, s[4:5]
	v_add_u32_e32 v60, 1, v60
	v_lshl_add_u64 v[58:59], v[58:59], 0, v[56:57]
	v_cmp_ne_u32_e32 vcc, 0x1100, v60
	s_nop 1
	v_cndmask_b32_e32 v60, 0, v60, vcc
	ds_read2_b64 v[26:29], v63 offset1:32
	v_and_b32_e32 v64, 0xfffffeff, v60
	v_and_b32_e32 v65, 0xffffefff, v60
	v_cmp_eq_u32_e32 vcc, 0, v64
	v_cmp_eq_u32_e64 s[2:3], s33, v65
	v_add_u32_e32 v63, 0x210, v63
	s_nop 0
	v_cndmask_b32_e64 v52, 1.0, 0, vcc
	v_cndmask_b32_e64 v54, 1.0, 0, s[2:3]
	s_waitcnt lgkmcnt(0)
	v_lshlrev_b32_e32 v6, 16, v26
	v_and_b32_e32 v7, 0xffff0000, v26
	v_lshlrev_b32_e32 v8, 16, v27
	v_and_b32_e32 v9, 0xffff0000, v27
	v_lshlrev_b32_e32 v18, 16, v28
	v_and_b32_e32 v19, 0xffff0000, v28
	v_lshlrev_b32_e32 v20, 16, v29
	v_and_b32_e32 v21, 0xffff0000, v29
	v_pk_fma_f32 v[30:31], v[146:147], v[14:15], v[158:159]
	v_pk_fma_f32 v[32:33], v[148:149], v[16:17], v[160:161]
	v_pk_mul_f32 v[38:39], v[52:53], v[22:23] op_sel_hi:[0,1]
	v_pk_mul_f32 v[40:41], v[52:53], v[24:25] op_sel_hi:[0,1]
	v_pk_fma_f32 v[30:31], v[142:143], v[38:39], v[30:31]
	v_pk_fma_f32 v[32:33], v[144:145], v[40:41], v[32:33]
	v_pk_mul_f32 v[38:39], v[54:55], v[18:19] op_sel_hi:[0,1]
	v_pk_mul_f32 v[40:41], v[54:55], v[20:21] op_sel_hi:[0,1]
	v_pk_fma_f32 v[30:31], v[150:151], v[38:39], v[30:31]
	v_pk_fma_f32 v[32:33], v[152:153], v[40:41], v[32:33]
	v_pk_fma_f32 v[34:35], v[134:135], v[2:3], v[154:155]
	v_pk_fma_f32 v[36:37], v[136:137], v[4:5], v[156:157]
	v_pk_mul_f32 v[38:39], v[52:53], v[10:11] op_sel_hi:[0,1]
	v_pk_mul_f32 v[40:41], v[52:53], v[12:13] op_sel_hi:[0,1]
	v_pk_fma_f32 v[34:35], v[130:131], v[38:39], v[34:35]
	v_pk_fma_f32 v[36:37], v[132:133], v[40:41], v[36:37]
	v_pk_mul_f32 v[38:39], v[54:55], v[6:7] op_sel_hi:[0,1]
	v_pk_mul_f32 v[40:41], v[54:55], v[8:9] op_sel_hi:[0,1]
	v_pk_fma_f32 v[34:35], v[138:139], v[38:39], v[34:35]
	v_pk_fma_f32 v[36:37], v[140:141], v[40:41], v[36:37]
	v_mul_f32_e32 v42, 0xbfb8aa3b, v30
	v_exp_f32_e32 v42, v42
	v_mul_f32_e32 v43, 0xbfb8aa3b, v31
	v_exp_f32_e32 v43, v43
	v_mul_f32_e32 v44, 0xbfb8aa3b, v32
	v_exp_f32_e32 v44, v44
	v_mul_f32_e32 v45, 0xbfb8aa3b, v33
	v_exp_f32_e32 v45, v45
	v_pk_add_f32 v[42:43], v[42:43], 1.0 op_sel_hi:[1,0]
	v_pk_add_f32 v[44:45], v[44:45], 1.0 op_sel_hi:[1,0]
	v_rcp_f32_e32 v46, v42
	v_rcp_f32_e32 v47, v43
	v_rcp_f32_e32 v48, v44
	v_rcp_f32_e32 v49, v45
	v_mul_f32_e32 v46, v30, v46
	v_mul_f32_e32 v47, v31, v47
	v_mul_f32_e32 v48, v32, v48
	v_mul_f32_e32 v49, v33, v49
	v_pk_mul_f32 v[34:35], v[34:35], v[46:47]
	v_pk_mul_f32 v[36:37], v[36:37], v[48:49]
	v_cvt_pk_bf16_f32 v66, v34, v35
	v_cvt_pk_bf16_f32 v67, v36, v37
	v_cmp_gt_i32_e32 vcc, s33, v61
	v_cmp_gt_i32_e64 s[2:3], s14, v62
	v_add_u32_e32 v61, 1, v61
	v_add_u32_e32 v62, 1, v62
	s_and_b64 s[2:3], vcc, s[2:3]
	s_and_saveexec_b64 s[4:5], s[2:3]
	global_store_dwordx2 v[58:59], v[66:67], off
	s_or_b64 exec, exec, s[4:5]
	v_add_u32_e32 v60, 1, v60
	v_lshl_add_u64 v[58:59], v[58:59], 0, v[56:57]
	v_cmp_ne_u32_e32 vcc, 0x1100, v60
	s_nop 1
	v_cndmask_b32_e32 v60, 0, v60, vcc
	ds_read2_b64 v[26:29], v63 offset1:32
	v_and_b32_e32 v64, 0xfffffeff, v60
	v_and_b32_e32 v65, 0xffffefff, v60
	v_cmp_eq_u32_e32 vcc, 0, v64
	v_cmp_eq_u32_e64 s[2:3], s33, v65
	v_add_u32_e32 v63, 0x210, v63
	s_nop 0
	v_cndmask_b32_e64 v52, 1.0, 0, vcc
	v_cndmask_b32_e64 v54, 1.0, 0, s[2:3]
	s_waitcnt lgkmcnt(0)
	v_lshlrev_b32_e32 v10, 16, v26
	v_and_b32_e32 v11, 0xffff0000, v26
	v_lshlrev_b32_e32 v12, 16, v27
	v_and_b32_e32 v13, 0xffff0000, v27
	v_lshlrev_b32_e32 v22, 16, v28
	v_and_b32_e32 v23, 0xffff0000, v28
	v_lshlrev_b32_e32 v24, 16, v29
	v_and_b32_e32 v25, 0xffff0000, v29
	v_pk_fma_f32 v[30:31], v[146:147], v[18:19], v[158:159]
	v_pk_fma_f32 v[32:33], v[148:149], v[20:21], v[160:161]
	v_pk_mul_f32 v[38:39], v[52:53], v[14:15] op_sel_hi:[0,1]
	v_pk_mul_f32 v[40:41], v[52:53], v[16:17] op_sel_hi:[0,1]
	v_pk_fma_f32 v[30:31], v[142:143], v[38:39], v[30:31]
	v_pk_fma_f32 v[32:33], v[144:145], v[40:41], v[32:33]
	v_pk_mul_f32 v[38:39], v[54:55], v[22:23] op_sel_hi:[0,1]
	v_pk_mul_f32 v[40:41], v[54:55], v[24:25] op_sel_hi:[0,1]
	v_pk_fma_f32 v[30:31], v[150:151], v[38:39], v[30:31]
	v_pk_fma_f32 v[32:33], v[152:153], v[40:41], v[32:33]
	v_pk_fma_f32 v[34:35], v[134:135], v[6:7], v[154:155]
	v_pk_fma_f32 v[36:37], v[136:137], v[8:9], v[156:157]
	v_pk_mul_f32 v[38:39], v[52:53], v[2:3] op_sel_hi:[0,1]
	v_pk_mul_f32 v[40:41], v[52:53], v[4:5] op_sel_hi:[0,1]
	v_pk_fma_f32 v[34:35], v[130:131], v[38:39], v[34:35]
	v_pk_fma_f32 v[36:37], v[132:133], v[40:41], v[36:37]
	v_pk_mul_f32 v[38:39], v[54:55], v[10:11] op_sel_hi:[0,1]
	v_pk_mul_f32 v[40:41], v[54:55], v[12:13] op_sel_hi:[0,1]
	v_pk_fma_f32 v[34:35], v[138:139], v[38:39], v[34:35]
	v_pk_fma_f32 v[36:37], v[140:141], v[40:41], v[36:37]
	v_mul_f32_e32 v42, 0xbfb8aa3b, v30
	v_exp_f32_e32 v42, v42
	v_mul_f32_e32 v43, 0xbfb8aa3b, v31
	v_exp_f32_e32 v43, v43
	v_mul_f32_e32 v44, 0xbfb8aa3b, v32
	v_exp_f32_e32 v44, v44
	v_mul_f32_e32 v45, 0xbfb8aa3b, v33
	v_exp_f32_e32 v45, v45
	v_pk_add_f32 v[42:43], v[42:43], 1.0 op_sel_hi:[1,0]
	v_pk_add_f32 v[44:45], v[44:45], 1.0 op_sel_hi:[1,0]
	v_rcp_f32_e32 v46, v42
	v_rcp_f32_e32 v47, v43
	v_rcp_f32_e32 v48, v44
	v_rcp_f32_e32 v49, v45
	v_mul_f32_e32 v46, v30, v46
	v_mul_f32_e32 v47, v31, v47
	v_mul_f32_e32 v48, v32, v48
	v_mul_f32_e32 v49, v33, v49
	v_pk_mul_f32 v[34:35], v[34:35], v[46:47]
	v_pk_mul_f32 v[36:37], v[36:37], v[48:49]
	v_cvt_pk_bf16_f32 v66, v34, v35
	v_cvt_pk_bf16_f32 v67, v36, v37
	v_cmp_gt_i32_e32 vcc, s33, v61
	v_cmp_gt_i32_e64 s[2:3], s14, v62
	v_add_u32_e32 v61, 1, v61
	v_add_u32_e32 v62, 1, v62
	s_and_b64 s[2:3], vcc, s[2:3]
	s_and_saveexec_b64 s[4:5], s[2:3]
	global_store_dwordx2 v[58:59], v[66:67], off
	s_or_b64 exec, exec, s[4:5]
	v_add_u32_e32 v60, 1, v60
	v_lshl_add_u64 v[58:59], v[58:59], 0, v[56:57]
	v_cmp_ne_u32_e32 vcc, 0x1100, v60
	s_nop 1
	v_cndmask_b32_e32 v60, 0, v60, vcc
	ds_read2_b64 v[26:29], v63 offset1:32
	v_and_b32_e32 v64, 0xfffffeff, v60
	v_and_b32_e32 v65, 0xffffefff, v60
	v_cmp_eq_u32_e32 vcc, 0, v64
	v_cmp_eq_u32_e64 s[2:3], s33, v65
	v_add_u32_e32 v63, 0x210, v63
	s_nop 0
	v_cndmask_b32_e64 v52, 1.0, 0, vcc
	v_cndmask_b32_e64 v54, 1.0, 0, s[2:3]
	s_waitcnt lgkmcnt(0)
	v_lshlrev_b32_e32 v2, 16, v26
	v_and_b32_e32 v3, 0xffff0000, v26
	v_lshlrev_b32_e32 v4, 16, v27
	v_and_b32_e32 v5, 0xffff0000, v27
	v_lshlrev_b32_e32 v14, 16, v28
	v_and_b32_e32 v15, 0xffff0000, v28
	v_lshlrev_b32_e32 v16, 16, v29
	v_and_b32_e32 v17, 0xffff0000, v29
	v_pk_fma_f32 v[30:31], v[146:147], v[22:23], v[158:159]
	v_pk_fma_f32 v[32:33], v[148:149], v[24:25], v[160:161]
	v_pk_mul_f32 v[38:39], v[52:53], v[18:19] op_sel_hi:[0,1]
	v_pk_mul_f32 v[40:41], v[52:53], v[20:21] op_sel_hi:[0,1]
	v_pk_fma_f32 v[30:31], v[142:143], v[38:39], v[30:31]
	v_pk_fma_f32 v[32:33], v[144:145], v[40:41], v[32:33]
	v_pk_mul_f32 v[38:39], v[54:55], v[14:15] op_sel_hi:[0,1]
	v_pk_mul_f32 v[40:41], v[54:55], v[16:17] op_sel_hi:[0,1]
	v_pk_fma_f32 v[30:31], v[150:151], v[38:39], v[30:31]
	v_pk_fma_f32 v[32:33], v[152:153], v[40:41], v[32:33]
	v_pk_fma_f32 v[34:35], v[134:135], v[10:11], v[154:155]
	v_pk_fma_f32 v[36:37], v[136:137], v[12:13], v[156:157]
	v_pk_mul_f32 v[38:39], v[52:53], v[6:7] op_sel_hi:[0,1]
	v_pk_mul_f32 v[40:41], v[52:53], v[8:9] op_sel_hi:[0,1]
	v_pk_fma_f32 v[34:35], v[130:131], v[38:39], v[34:35]
	v_pk_fma_f32 v[36:37], v[132:133], v[40:41], v[36:37]
	v_pk_mul_f32 v[38:39], v[54:55], v[2:3] op_sel_hi:[0,1]
	v_pk_mul_f32 v[40:41], v[54:55], v[4:5] op_sel_hi:[0,1]
	v_pk_fma_f32 v[34:35], v[138:139], v[38:39], v[34:35]
	v_pk_fma_f32 v[36:37], v[140:141], v[40:41], v[36:37]
	v_mul_f32_e32 v42, 0xbfb8aa3b, v30
	v_exp_f32_e32 v42, v42
	v_mul_f32_e32 v43, 0xbfb8aa3b, v31
	v_exp_f32_e32 v43, v43
	v_mul_f32_e32 v44, 0xbfb8aa3b, v32
	v_exp_f32_e32 v44, v44
	v_mul_f32_e32 v45, 0xbfb8aa3b, v33
	v_exp_f32_e32 v45, v45
	v_pk_add_f32 v[42:43], v[42:43], 1.0 op_sel_hi:[1,0]
	v_pk_add_f32 v[44:45], v[44:45], 1.0 op_sel_hi:[1,0]
	v_rcp_f32_e32 v46, v42
	v_rcp_f32_e32 v47, v43
	v_rcp_f32_e32 v48, v44
	v_rcp_f32_e32 v49, v45
	v_mul_f32_e32 v46, v30, v46
	v_mul_f32_e32 v47, v31, v47
	v_mul_f32_e32 v48, v32, v48
	v_mul_f32_e32 v49, v33, v49
	v_pk_mul_f32 v[34:35], v[34:35], v[46:47]
	v_pk_mul_f32 v[36:37], v[36:37], v[48:49]
	v_cvt_pk_bf16_f32 v66, v34, v35
	v_cvt_pk_bf16_f32 v67, v36, v37
	v_cmp_gt_i32_e32 vcc, s33, v61
	v_cmp_gt_i32_e64 s[2:3], s14, v62
	v_add_u32_e32 v61, 1, v61
	v_add_u32_e32 v62, 1, v62
	s_and_b64 s[2:3], vcc, s[2:3]
	s_and_saveexec_b64 s[4:5], s[2:3]
	global_store_dwordx2 v[58:59], v[66:67], off
	s_or_b64 exec, exec, s[4:5]
	v_add_u32_e32 v60, 1, v60
	v_lshl_add_u64 v[58:59], v[58:59], 0, v[56:57]
	v_cmp_ne_u32_e32 vcc, 0x1100, v60
	s_nop 1
	v_cndmask_b32_e32 v60, 0, v60, vcc
	ds_read2_b64 v[26:29], v63 offset1:32
	v_and_b32_e32 v64, 0xfffffeff, v60
	v_and_b32_e32 v65, 0xffffefff, v60
	v_cmp_eq_u32_e32 vcc, 0, v64
	v_cmp_eq_u32_e64 s[2:3], s33, v65
	v_add_u32_e32 v63, 0x210, v63
	s_nop 0
	v_cndmask_b32_e64 v52, 1.0, 0, vcc
	v_cndmask_b32_e64 v54, 1.0, 0, s[2:3]
	s_waitcnt lgkmcnt(0)
	v_lshlrev_b32_e32 v6, 16, v26
	v_and_b32_e32 v7, 0xffff0000, v26
	v_lshlrev_b32_e32 v8, 16, v27
	v_and_b32_e32 v9, 0xffff0000, v27
	v_lshlrev_b32_e32 v18, 16, v28
	v_and_b32_e32 v19, 0xffff0000, v28
	v_lshlrev_b32_e32 v20, 16, v29
	v_and_b32_e32 v21, 0xffff0000, v29
	v_pk_fma_f32 v[30:31], v[146:147], v[14:15], v[158:159]
	v_pk_fma_f32 v[32:33], v[148:149], v[16:17], v[160:161]
	v_pk_mul_f32 v[38:39], v[52:53], v[22:23] op_sel_hi:[0,1]
	v_pk_mul_f32 v[40:41], v[52:53], v[24:25] op_sel_hi:[0,1]
	v_pk_fma_f32 v[30:31], v[142:143], v[38:39], v[30:31]
	v_pk_fma_f32 v[32:33], v[144:145], v[40:41], v[32:33]
	v_pk_mul_f32 v[38:39], v[54:55], v[18:19] op_sel_hi:[0,1]
	v_pk_mul_f32 v[40:41], v[54:55], v[20:21] op_sel_hi:[0,1]
	v_pk_fma_f32 v[30:31], v[150:151], v[38:39], v[30:31]
	v_pk_fma_f32 v[32:33], v[152:153], v[40:41], v[32:33]
	v_pk_fma_f32 v[34:35], v[134:135], v[2:3], v[154:155]
	v_pk_fma_f32 v[36:37], v[136:137], v[4:5], v[156:157]
	v_pk_mul_f32 v[38:39], v[52:53], v[10:11] op_sel_hi:[0,1]
	v_pk_mul_f32 v[40:41], v[52:53], v[12:13] op_sel_hi:[0,1]
	v_pk_fma_f32 v[34:35], v[130:131], v[38:39], v[34:35]
	v_pk_fma_f32 v[36:37], v[132:133], v[40:41], v[36:37]
	v_pk_mul_f32 v[38:39], v[54:55], v[6:7] op_sel_hi:[0,1]
	v_pk_mul_f32 v[40:41], v[54:55], v[8:9] op_sel_hi:[0,1]
	v_pk_fma_f32 v[34:35], v[138:139], v[38:39], v[34:35]
	v_pk_fma_f32 v[36:37], v[140:141], v[40:41], v[36:37]
	v_mul_f32_e32 v42, 0xbfb8aa3b, v30
	v_exp_f32_e32 v42, v42
	v_mul_f32_e32 v43, 0xbfb8aa3b, v31
	v_exp_f32_e32 v43, v43
	v_mul_f32_e32 v44, 0xbfb8aa3b, v32
	v_exp_f32_e32 v44, v44
	v_mul_f32_e32 v45, 0xbfb8aa3b, v33
	v_exp_f32_e32 v45, v45
	v_pk_add_f32 v[42:43], v[42:43], 1.0 op_sel_hi:[1,0]
	v_pk_add_f32 v[44:45], v[44:45], 1.0 op_sel_hi:[1,0]
	v_rcp_f32_e32 v46, v42
	v_rcp_f32_e32 v47, v43
	v_rcp_f32_e32 v48, v44
	v_rcp_f32_e32 v49, v45
	v_mul_f32_e32 v46, v30, v46
	v_mul_f32_e32 v47, v31, v47
	v_mul_f32_e32 v48, v32, v48
	v_mul_f32_e32 v49, v33, v49
	v_pk_mul_f32 v[34:35], v[34:35], v[46:47]
	v_pk_mul_f32 v[36:37], v[36:37], v[48:49]
	v_cvt_pk_bf16_f32 v66, v34, v35
	v_cvt_pk_bf16_f32 v67, v36, v37
	v_cmp_gt_i32_e32 vcc, s33, v61
	v_cmp_gt_i32_e64 s[2:3], s14, v62
	v_add_u32_e32 v61, 1, v61
	v_add_u32_e32 v62, 1, v62
	s_and_b64 s[2:3], vcc, s[2:3]
	s_and_saveexec_b64 s[4:5], s[2:3]
	global_store_dwordx2 v[58:59], v[66:67], off
	s_or_b64 exec, exec, s[4:5]
	v_add_u32_e32 v60, 1, v60
	v_lshl_add_u64 v[58:59], v[58:59], 0, v[56:57]
	v_cmp_ne_u32_e32 vcc, 0x1100, v60
	s_nop 1
	v_cndmask_b32_e32 v60, 0, v60, vcc
	ds_read2_b64 v[26:29], v63 offset1:32
	v_and_b32_e32 v64, 0xfffffeff, v60
	v_and_b32_e32 v65, 0xffffefff, v60
	v_cmp_eq_u32_e32 vcc, 0, v64
	v_cmp_eq_u32_e64 s[2:3], s33, v65
	v_add_u32_e32 v63, 0x210, v63
	s_nop 0
	v_cndmask_b32_e64 v52, 1.0, 0, vcc
	v_cndmask_b32_e64 v54, 1.0, 0, s[2:3]
	s_waitcnt lgkmcnt(0)
	v_lshlrev_b32_e32 v10, 16, v26
	v_and_b32_e32 v11, 0xffff0000, v26
	v_lshlrev_b32_e32 v12, 16, v27
	v_and_b32_e32 v13, 0xffff0000, v27
	v_lshlrev_b32_e32 v22, 16, v28
	v_and_b32_e32 v23, 0xffff0000, v28
	v_lshlrev_b32_e32 v24, 16, v29
	v_and_b32_e32 v25, 0xffff0000, v29
	v_pk_fma_f32 v[30:31], v[146:147], v[18:19], v[158:159]
	v_pk_fma_f32 v[32:33], v[148:149], v[20:21], v[160:161]
	v_pk_mul_f32 v[38:39], v[52:53], v[14:15] op_sel_hi:[0,1]
	v_pk_mul_f32 v[40:41], v[52:53], v[16:17] op_sel_hi:[0,1]
	v_pk_fma_f32 v[30:31], v[142:143], v[38:39], v[30:31]
	v_pk_fma_f32 v[32:33], v[144:145], v[40:41], v[32:33]
	v_pk_mul_f32 v[38:39], v[54:55], v[22:23] op_sel_hi:[0,1]
	v_pk_mul_f32 v[40:41], v[54:55], v[24:25] op_sel_hi:[0,1]
	v_pk_fma_f32 v[30:31], v[150:151], v[38:39], v[30:31]
	v_pk_fma_f32 v[32:33], v[152:153], v[40:41], v[32:33]
	v_pk_fma_f32 v[34:35], v[134:135], v[6:7], v[154:155]
	v_pk_fma_f32 v[36:37], v[136:137], v[8:9], v[156:157]
	v_pk_mul_f32 v[38:39], v[52:53], v[2:3] op_sel_hi:[0,1]
	v_pk_mul_f32 v[40:41], v[52:53], v[4:5] op_sel_hi:[0,1]
	v_pk_fma_f32 v[34:35], v[130:131], v[38:39], v[34:35]
	v_pk_fma_f32 v[36:37], v[132:133], v[40:41], v[36:37]
	v_pk_mul_f32 v[38:39], v[54:55], v[10:11] op_sel_hi:[0,1]
	v_pk_mul_f32 v[40:41], v[54:55], v[12:13] op_sel_hi:[0,1]
	v_pk_fma_f32 v[34:35], v[138:139], v[38:39], v[34:35]
	v_pk_fma_f32 v[36:37], v[140:141], v[40:41], v[36:37]
	v_mul_f32_e32 v42, 0xbfb8aa3b, v30
	v_exp_f32_e32 v42, v42
	v_mul_f32_e32 v43, 0xbfb8aa3b, v31
	v_exp_f32_e32 v43, v43
	v_mul_f32_e32 v44, 0xbfb8aa3b, v32
	v_exp_f32_e32 v44, v44
	v_mul_f32_e32 v45, 0xbfb8aa3b, v33
	v_exp_f32_e32 v45, v45
	v_pk_add_f32 v[42:43], v[42:43], 1.0 op_sel_hi:[1,0]
	v_pk_add_f32 v[44:45], v[44:45], 1.0 op_sel_hi:[1,0]
	v_rcp_f32_e32 v46, v42
	v_rcp_f32_e32 v47, v43
	v_rcp_f32_e32 v48, v44
	v_rcp_f32_e32 v49, v45
	v_mul_f32_e32 v46, v30, v46
	v_mul_f32_e32 v47, v31, v47
	v_mul_f32_e32 v48, v32, v48
	v_mul_f32_e32 v49, v33, v49
	v_pk_mul_f32 v[34:35], v[34:35], v[46:47]
	v_pk_mul_f32 v[36:37], v[36:37], v[48:49]
	v_cvt_pk_bf16_f32 v66, v34, v35
	v_cvt_pk_bf16_f32 v67, v36, v37
	v_cmp_gt_i32_e32 vcc, s33, v61
	v_cmp_gt_i32_e64 s[2:3], s14, v62
	v_add_u32_e32 v61, 1, v61
	v_add_u32_e32 v62, 1, v62
	s_and_b64 s[2:3], vcc, s[2:3]
	s_and_saveexec_b64 s[4:5], s[2:3]
	global_store_dwordx2 v[58:59], v[66:67], off
	s_or_b64 exec, exec, s[4:5]
	v_add_u32_e32 v60, 1, v60
	v_lshl_add_u64 v[58:59], v[58:59], 0, v[56:57]
	v_cmp_ne_u32_e32 vcc, 0x1100, v60
	s_nop 1
	v_cndmask_b32_e32 v60, 0, v60, vcc
	ds_read2_b64 v[26:29], v63 offset1:32
	v_and_b32_e32 v64, 0xfffffeff, v60
	v_and_b32_e32 v65, 0xffffefff, v60
	v_cmp_eq_u32_e32 vcc, 0, v64
	v_cmp_eq_u32_e64 s[2:3], s33, v65
	v_add_u32_e32 v63, 0x210, v63
	s_nop 0
	v_cndmask_b32_e64 v52, 1.0, 0, vcc
	v_cndmask_b32_e64 v54, 1.0, 0, s[2:3]
	s_waitcnt lgkmcnt(0)
	v_lshlrev_b32_e32 v2, 16, v26
	v_and_b32_e32 v3, 0xffff0000, v26
	v_lshlrev_b32_e32 v4, 16, v27
	v_and_b32_e32 v5, 0xffff0000, v27
	v_lshlrev_b32_e32 v14, 16, v28
	v_and_b32_e32 v15, 0xffff0000, v28
	v_lshlrev_b32_e32 v16, 16, v29
	v_and_b32_e32 v17, 0xffff0000, v29
	v_pk_fma_f32 v[30:31], v[146:147], v[22:23], v[158:159]
	v_pk_fma_f32 v[32:33], v[148:149], v[24:25], v[160:161]
	v_pk_mul_f32 v[38:39], v[52:53], v[18:19] op_sel_hi:[0,1]
	v_pk_mul_f32 v[40:41], v[52:53], v[20:21] op_sel_hi:[0,1]
	v_pk_fma_f32 v[30:31], v[142:143], v[38:39], v[30:31]
	v_pk_fma_f32 v[32:33], v[144:145], v[40:41], v[32:33]
	v_pk_mul_f32 v[38:39], v[54:55], v[14:15] op_sel_hi:[0,1]
	v_pk_mul_f32 v[40:41], v[54:55], v[16:17] op_sel_hi:[0,1]
	v_pk_fma_f32 v[30:31], v[150:151], v[38:39], v[30:31]
	v_pk_fma_f32 v[32:33], v[152:153], v[40:41], v[32:33]
	v_pk_fma_f32 v[34:35], v[134:135], v[10:11], v[154:155]
	v_pk_fma_f32 v[36:37], v[136:137], v[12:13], v[156:157]
	v_pk_mul_f32 v[38:39], v[52:53], v[6:7] op_sel_hi:[0,1]
	v_pk_mul_f32 v[40:41], v[52:53], v[8:9] op_sel_hi:[0,1]
	v_pk_fma_f32 v[34:35], v[130:131], v[38:39], v[34:35]
	v_pk_fma_f32 v[36:37], v[132:133], v[40:41], v[36:37]
	v_pk_mul_f32 v[38:39], v[54:55], v[2:3] op_sel_hi:[0,1]
	v_pk_mul_f32 v[40:41], v[54:55], v[4:5] op_sel_hi:[0,1]
	v_pk_fma_f32 v[34:35], v[138:139], v[38:39], v[34:35]
	v_pk_fma_f32 v[36:37], v[140:141], v[40:41], v[36:37]
	v_mul_f32_e32 v42, 0xbfb8aa3b, v30
	v_exp_f32_e32 v42, v42
	v_mul_f32_e32 v43, 0xbfb8aa3b, v31
	v_exp_f32_e32 v43, v43
	v_mul_f32_e32 v44, 0xbfb8aa3b, v32
	v_exp_f32_e32 v44, v44
	v_mul_f32_e32 v45, 0xbfb8aa3b, v33
	v_exp_f32_e32 v45, v45
	v_pk_add_f32 v[42:43], v[42:43], 1.0 op_sel_hi:[1,0]
	v_pk_add_f32 v[44:45], v[44:45], 1.0 op_sel_hi:[1,0]
	v_rcp_f32_e32 v46, v42
	v_rcp_f32_e32 v47, v43
	v_rcp_f32_e32 v48, v44
	v_rcp_f32_e32 v49, v45
	v_mul_f32_e32 v46, v30, v46
	v_mul_f32_e32 v47, v31, v47
	v_mul_f32_e32 v48, v32, v48
	v_mul_f32_e32 v49, v33, v49
	v_pk_mul_f32 v[34:35], v[34:35], v[46:47]
	v_pk_mul_f32 v[36:37], v[36:37], v[48:49]
	v_cvt_pk_bf16_f32 v66, v34, v35
	v_cvt_pk_bf16_f32 v67, v36, v37
	v_cmp_gt_i32_e32 vcc, s33, v61
	v_cmp_gt_i32_e64 s[2:3], s14, v62
	v_add_u32_e32 v61, 1, v61
	v_add_u32_e32 v62, 1, v62
	s_and_b64 s[2:3], vcc, s[2:3]
	s_and_saveexec_b64 s[4:5], s[2:3]
	global_store_dwordx2 v[58:59], v[66:67], off
	s_or_b64 exec, exec, s[4:5]
	v_add_u32_e32 v60, 1, v60
	v_lshl_add_u64 v[58:59], v[58:59], 0, v[56:57]
	v_cmp_ne_u32_e32 vcc, 0x1100, v60
	s_nop 1
	v_cndmask_b32_e32 v60, 0, v60, vcc
	ds_read2_b64 v[26:29], v63 offset1:32
	v_and_b32_e32 v64, 0xfffffeff, v60
	v_and_b32_e32 v65, 0xffffefff, v60
	v_cmp_eq_u32_e32 vcc, 0, v64
	v_cmp_eq_u32_e64 s[2:3], s33, v65
	v_add_u32_e32 v63, 0x210, v63
	s_nop 0
	v_cndmask_b32_e64 v52, 1.0, 0, vcc
	v_cndmask_b32_e64 v54, 1.0, 0, s[2:3]
	s_waitcnt lgkmcnt(0)
	v_lshlrev_b32_e32 v6, 16, v26
	v_and_b32_e32 v7, 0xffff0000, v26
	v_lshlrev_b32_e32 v8, 16, v27
	v_and_b32_e32 v9, 0xffff0000, v27
	v_lshlrev_b32_e32 v18, 16, v28
	v_and_b32_e32 v19, 0xffff0000, v28
	v_lshlrev_b32_e32 v20, 16, v29
	v_and_b32_e32 v21, 0xffff0000, v29
	v_pk_fma_f32 v[30:31], v[146:147], v[14:15], v[158:159]
	v_pk_fma_f32 v[32:33], v[148:149], v[16:17], v[160:161]
	v_pk_mul_f32 v[38:39], v[52:53], v[22:23] op_sel_hi:[0,1]
	v_pk_mul_f32 v[40:41], v[52:53], v[24:25] op_sel_hi:[0,1]
	v_pk_fma_f32 v[30:31], v[142:143], v[38:39], v[30:31]
	v_pk_fma_f32 v[32:33], v[144:145], v[40:41], v[32:33]
	v_pk_mul_f32 v[38:39], v[54:55], v[18:19] op_sel_hi:[0,1]
	v_pk_mul_f32 v[40:41], v[54:55], v[20:21] op_sel_hi:[0,1]
	v_pk_fma_f32 v[30:31], v[150:151], v[38:39], v[30:31]
	v_pk_fma_f32 v[32:33], v[152:153], v[40:41], v[32:33]
	v_pk_fma_f32 v[34:35], v[134:135], v[2:3], v[154:155]
	v_pk_fma_f32 v[36:37], v[136:137], v[4:5], v[156:157]
	v_pk_mul_f32 v[38:39], v[52:53], v[10:11] op_sel_hi:[0,1]
	v_pk_mul_f32 v[40:41], v[52:53], v[12:13] op_sel_hi:[0,1]
	v_pk_fma_f32 v[34:35], v[130:131], v[38:39], v[34:35]
	v_pk_fma_f32 v[36:37], v[132:133], v[40:41], v[36:37]
	v_pk_mul_f32 v[38:39], v[54:55], v[6:7] op_sel_hi:[0,1]
	v_pk_mul_f32 v[40:41], v[54:55], v[8:9] op_sel_hi:[0,1]
	v_pk_fma_f32 v[34:35], v[138:139], v[38:39], v[34:35]
	v_pk_fma_f32 v[36:37], v[140:141], v[40:41], v[36:37]
	v_mul_f32_e32 v42, 0xbfb8aa3b, v30
	v_exp_f32_e32 v42, v42
	v_mul_f32_e32 v43, 0xbfb8aa3b, v31
	v_exp_f32_e32 v43, v43
	v_mul_f32_e32 v44, 0xbfb8aa3b, v32
	v_exp_f32_e32 v44, v44
	v_mul_f32_e32 v45, 0xbfb8aa3b, v33
	v_exp_f32_e32 v45, v45
	v_pk_add_f32 v[42:43], v[42:43], 1.0 op_sel_hi:[1,0]
	v_pk_add_f32 v[44:45], v[44:45], 1.0 op_sel_hi:[1,0]
	v_rcp_f32_e32 v46, v42
	v_rcp_f32_e32 v47, v43
	v_rcp_f32_e32 v48, v44
	v_rcp_f32_e32 v49, v45
	v_mul_f32_e32 v46, v30, v46
	v_mul_f32_e32 v47, v31, v47
	v_mul_f32_e32 v48, v32, v48
	v_mul_f32_e32 v49, v33, v49
	v_pk_mul_f32 v[34:35], v[34:35], v[46:47]
	v_pk_mul_f32 v[36:37], v[36:37], v[48:49]
	v_cvt_pk_bf16_f32 v66, v34, v35
	v_cvt_pk_bf16_f32 v67, v36, v37
	v_cmp_gt_i32_e32 vcc, s33, v61
	v_cmp_gt_i32_e64 s[2:3], s14, v62
	v_add_u32_e32 v61, 1, v61
	v_add_u32_e32 v62, 1, v62
	s_and_b64 s[2:3], vcc, s[2:3]
	s_and_saveexec_b64 s[4:5], s[2:3]
	global_store_dwordx2 v[58:59], v[66:67], off
	s_or_b64 exec, exec, s[4:5]
	v_add_u32_e32 v60, 1, v60
	v_lshl_add_u64 v[58:59], v[58:59], 0, v[56:57]
	v_cmp_ne_u32_e32 vcc, 0x1100, v60
	s_nop 1
	v_cndmask_b32_e32 v60, 0, v60, vcc
	ds_read2_b64 v[26:29], v63 offset1:32
	v_and_b32_e32 v64, 0xfffffeff, v60
	v_and_b32_e32 v65, 0xffffefff, v60
	v_cmp_eq_u32_e32 vcc, 0, v64
	v_cmp_eq_u32_e64 s[2:3], s33, v65
	v_add_u32_e32 v63, 0x210, v63
	s_nop 0
	v_cndmask_b32_e64 v52, 1.0, 0, vcc
	v_cndmask_b32_e64 v54, 1.0, 0, s[2:3]
	s_waitcnt lgkmcnt(0)
	v_lshlrev_b32_e32 v10, 16, v26
	v_and_b32_e32 v11, 0xffff0000, v26
	v_lshlrev_b32_e32 v12, 16, v27
	v_and_b32_e32 v13, 0xffff0000, v27
	v_lshlrev_b32_e32 v22, 16, v28
	v_and_b32_e32 v23, 0xffff0000, v28
	v_lshlrev_b32_e32 v24, 16, v29
	v_and_b32_e32 v25, 0xffff0000, v29
	v_pk_fma_f32 v[30:31], v[146:147], v[18:19], v[158:159]
	v_pk_fma_f32 v[32:33], v[148:149], v[20:21], v[160:161]
	v_pk_mul_f32 v[38:39], v[52:53], v[14:15] op_sel_hi:[0,1]
	v_pk_mul_f32 v[40:41], v[52:53], v[16:17] op_sel_hi:[0,1]
	v_pk_fma_f32 v[30:31], v[142:143], v[38:39], v[30:31]
	v_pk_fma_f32 v[32:33], v[144:145], v[40:41], v[32:33]
	v_pk_mul_f32 v[38:39], v[54:55], v[22:23] op_sel_hi:[0,1]
	v_pk_mul_f32 v[40:41], v[54:55], v[24:25] op_sel_hi:[0,1]
	v_pk_fma_f32 v[30:31], v[150:151], v[38:39], v[30:31]
	v_pk_fma_f32 v[32:33], v[152:153], v[40:41], v[32:33]
	v_pk_fma_f32 v[34:35], v[134:135], v[6:7], v[154:155]
	v_pk_fma_f32 v[36:37], v[136:137], v[8:9], v[156:157]
	v_pk_mul_f32 v[38:39], v[52:53], v[2:3] op_sel_hi:[0,1]
	v_pk_mul_f32 v[40:41], v[52:53], v[4:5] op_sel_hi:[0,1]
	v_pk_fma_f32 v[34:35], v[130:131], v[38:39], v[34:35]
	v_pk_fma_f32 v[36:37], v[132:133], v[40:41], v[36:37]
	v_pk_mul_f32 v[38:39], v[54:55], v[10:11] op_sel_hi:[0,1]
	v_pk_mul_f32 v[40:41], v[54:55], v[12:13] op_sel_hi:[0,1]
	v_pk_fma_f32 v[34:35], v[138:139], v[38:39], v[34:35]
	v_pk_fma_f32 v[36:37], v[140:141], v[40:41], v[36:37]
	v_mul_f32_e32 v42, 0xbfb8aa3b, v30
	v_exp_f32_e32 v42, v42
	v_mul_f32_e32 v43, 0xbfb8aa3b, v31
	v_exp_f32_e32 v43, v43
	v_mul_f32_e32 v44, 0xbfb8aa3b, v32
	v_exp_f32_e32 v44, v44
	v_mul_f32_e32 v45, 0xbfb8aa3b, v33
	v_exp_f32_e32 v45, v45
	v_pk_add_f32 v[42:43], v[42:43], 1.0 op_sel_hi:[1,0]
	v_pk_add_f32 v[44:45], v[44:45], 1.0 op_sel_hi:[1,0]
	v_rcp_f32_e32 v46, v42
	v_rcp_f32_e32 v47, v43
	v_rcp_f32_e32 v48, v44
	v_rcp_f32_e32 v49, v45
	v_mul_f32_e32 v46, v30, v46
	v_mul_f32_e32 v47, v31, v47
	v_mul_f32_e32 v48, v32, v48
	v_mul_f32_e32 v49, v33, v49
	v_pk_mul_f32 v[34:35], v[34:35], v[46:47]
	v_pk_mul_f32 v[36:37], v[36:37], v[48:49]
	v_cvt_pk_bf16_f32 v66, v34, v35
	v_cvt_pk_bf16_f32 v67, v36, v37
	v_cmp_gt_i32_e32 vcc, s33, v61
	v_cmp_gt_i32_e64 s[2:3], s14, v62
	v_add_u32_e32 v61, 1, v61
	v_add_u32_e32 v62, 1, v62
	s_and_b64 s[2:3], vcc, s[2:3]
	s_and_saveexec_b64 s[4:5], s[2:3]
	global_store_dwordx2 v[58:59], v[66:67], off
	s_or_b64 exec, exec, s[4:5]
	v_add_u32_e32 v60, 1, v60
	v_lshl_add_u64 v[58:59], v[58:59], 0, v[56:57]
	v_cmp_ne_u32_e32 vcc, 0x1100, v60
	s_nop 1
	v_cndmask_b32_e32 v60, 0, v60, vcc
	ds_read2_b64 v[26:29], v63 offset1:32
	v_and_b32_e32 v64, 0xfffffeff, v60
	v_and_b32_e32 v65, 0xffffefff, v60
	v_cmp_eq_u32_e32 vcc, 0, v64
	v_cmp_eq_u32_e64 s[2:3], s33, v65
	v_add_u32_e32 v63, 0x210, v63
	s_nop 0
	v_cndmask_b32_e64 v52, 1.0, 0, vcc
	v_cndmask_b32_e64 v54, 1.0, 0, s[2:3]
	s_waitcnt lgkmcnt(0)
	v_lshlrev_b32_e32 v2, 16, v26
	v_and_b32_e32 v3, 0xffff0000, v26
	v_lshlrev_b32_e32 v4, 16, v27
	v_and_b32_e32 v5, 0xffff0000, v27
	v_lshlrev_b32_e32 v14, 16, v28
	v_and_b32_e32 v15, 0xffff0000, v28
	v_lshlrev_b32_e32 v16, 16, v29
	v_and_b32_e32 v17, 0xffff0000, v29
	v_pk_fma_f32 v[30:31], v[146:147], v[22:23], v[158:159]
	v_pk_fma_f32 v[32:33], v[148:149], v[24:25], v[160:161]
	v_pk_mul_f32 v[38:39], v[52:53], v[18:19] op_sel_hi:[0,1]
	v_pk_mul_f32 v[40:41], v[52:53], v[20:21] op_sel_hi:[0,1]
	v_pk_fma_f32 v[30:31], v[142:143], v[38:39], v[30:31]
	v_pk_fma_f32 v[32:33], v[144:145], v[40:41], v[32:33]
	v_pk_mul_f32 v[38:39], v[54:55], v[14:15] op_sel_hi:[0,1]
	v_pk_mul_f32 v[40:41], v[54:55], v[16:17] op_sel_hi:[0,1]
	v_pk_fma_f32 v[30:31], v[150:151], v[38:39], v[30:31]
	v_pk_fma_f32 v[32:33], v[152:153], v[40:41], v[32:33]
	v_pk_fma_f32 v[34:35], v[134:135], v[10:11], v[154:155]
	v_pk_fma_f32 v[36:37], v[136:137], v[12:13], v[156:157]
	v_pk_mul_f32 v[38:39], v[52:53], v[6:7] op_sel_hi:[0,1]
	v_pk_mul_f32 v[40:41], v[52:53], v[8:9] op_sel_hi:[0,1]
	v_pk_fma_f32 v[34:35], v[130:131], v[38:39], v[34:35]
	v_pk_fma_f32 v[36:37], v[132:133], v[40:41], v[36:37]
	v_pk_mul_f32 v[38:39], v[54:55], v[2:3] op_sel_hi:[0,1]
	v_pk_mul_f32 v[40:41], v[54:55], v[4:5] op_sel_hi:[0,1]
	v_pk_fma_f32 v[34:35], v[138:139], v[38:39], v[34:35]
	v_pk_fma_f32 v[36:37], v[140:141], v[40:41], v[36:37]
	v_mul_f32_e32 v42, 0xbfb8aa3b, v30
	v_exp_f32_e32 v42, v42
	v_mul_f32_e32 v43, 0xbfb8aa3b, v31
	v_exp_f32_e32 v43, v43
	v_mul_f32_e32 v44, 0xbfb8aa3b, v32
	v_exp_f32_e32 v44, v44
	v_mul_f32_e32 v45, 0xbfb8aa3b, v33
	v_exp_f32_e32 v45, v45
	v_pk_add_f32 v[42:43], v[42:43], 1.0 op_sel_hi:[1,0]
	v_pk_add_f32 v[44:45], v[44:45], 1.0 op_sel_hi:[1,0]
	v_rcp_f32_e32 v46, v42
	v_rcp_f32_e32 v47, v43
	v_rcp_f32_e32 v48, v44
	v_rcp_f32_e32 v49, v45
	v_mul_f32_e32 v46, v30, v46
	v_mul_f32_e32 v47, v31, v47
	v_mul_f32_e32 v48, v32, v48
	v_mul_f32_e32 v49, v33, v49
	v_pk_mul_f32 v[34:35], v[34:35], v[46:47]
	v_pk_mul_f32 v[36:37], v[36:37], v[48:49]
	v_cvt_pk_bf16_f32 v66, v34, v35
	v_cvt_pk_bf16_f32 v67, v36, v37
	v_cmp_gt_i32_e32 vcc, s33, v61
	v_cmp_gt_i32_e64 s[2:3], s14, v62
	v_add_u32_e32 v61, 1, v61
	v_add_u32_e32 v62, 1, v62
	s_and_b64 s[2:3], vcc, s[2:3]
	s_and_saveexec_b64 s[4:5], s[2:3]
	global_store_dwordx2 v[58:59], v[66:67], off
	s_or_b64 exec, exec, s[4:5]
	v_add_u32_e32 v60, 1, v60
	v_lshl_add_u64 v[58:59], v[58:59], 0, v[56:57]
	v_cmp_ne_u32_e32 vcc, 0x1100, v60
	s_nop 1
	v_cndmask_b32_e32 v60, 0, v60, vcc
	ds_read2_b64 v[26:29], v63 offset1:32
	v_and_b32_e32 v64, 0xfffffeff, v60
	v_and_b32_e32 v65, 0xffffefff, v60
	v_cmp_eq_u32_e32 vcc, 0, v64
	v_cmp_eq_u32_e64 s[2:3], s33, v65
	v_add_u32_e32 v63, 0x210, v63
	s_nop 0
	v_cndmask_b32_e64 v52, 1.0, 0, vcc
	v_cndmask_b32_e64 v54, 1.0, 0, s[2:3]
	s_waitcnt lgkmcnt(0)
	v_lshlrev_b32_e32 v6, 16, v26
	v_and_b32_e32 v7, 0xffff0000, v26
	v_lshlrev_b32_e32 v8, 16, v27
	v_and_b32_e32 v9, 0xffff0000, v27
	v_lshlrev_b32_e32 v18, 16, v28
	v_and_b32_e32 v19, 0xffff0000, v28
	v_lshlrev_b32_e32 v20, 16, v29
	v_and_b32_e32 v21, 0xffff0000, v29
	v_pk_fma_f32 v[30:31], v[146:147], v[14:15], v[158:159]
	v_pk_fma_f32 v[32:33], v[148:149], v[16:17], v[160:161]
	v_pk_mul_f32 v[38:39], v[52:53], v[22:23] op_sel_hi:[0,1]
	v_pk_mul_f32 v[40:41], v[52:53], v[24:25] op_sel_hi:[0,1]
	v_pk_fma_f32 v[30:31], v[142:143], v[38:39], v[30:31]
	v_pk_fma_f32 v[32:33], v[144:145], v[40:41], v[32:33]
	v_pk_mul_f32 v[38:39], v[54:55], v[18:19] op_sel_hi:[0,1]
	v_pk_mul_f32 v[40:41], v[54:55], v[20:21] op_sel_hi:[0,1]
	v_pk_fma_f32 v[30:31], v[150:151], v[38:39], v[30:31]
	v_pk_fma_f32 v[32:33], v[152:153], v[40:41], v[32:33]
	v_pk_fma_f32 v[34:35], v[134:135], v[2:3], v[154:155]
	v_pk_fma_f32 v[36:37], v[136:137], v[4:5], v[156:157]
	v_pk_mul_f32 v[38:39], v[52:53], v[10:11] op_sel_hi:[0,1]
	v_pk_mul_f32 v[40:41], v[52:53], v[12:13] op_sel_hi:[0,1]
	v_pk_fma_f32 v[34:35], v[130:131], v[38:39], v[34:35]
	v_pk_fma_f32 v[36:37], v[132:133], v[40:41], v[36:37]
	v_pk_mul_f32 v[38:39], v[54:55], v[6:7] op_sel_hi:[0,1]
	v_pk_mul_f32 v[40:41], v[54:55], v[8:9] op_sel_hi:[0,1]
	v_pk_fma_f32 v[34:35], v[138:139], v[38:39], v[34:35]
	v_pk_fma_f32 v[36:37], v[140:141], v[40:41], v[36:37]
	v_mul_f32_e32 v42, 0xbfb8aa3b, v30
	v_exp_f32_e32 v42, v42
	v_mul_f32_e32 v43, 0xbfb8aa3b, v31
	v_exp_f32_e32 v43, v43
	v_mul_f32_e32 v44, 0xbfb8aa3b, v32
	v_exp_f32_e32 v44, v44
	v_mul_f32_e32 v45, 0xbfb8aa3b, v33
	v_exp_f32_e32 v45, v45
	v_pk_add_f32 v[42:43], v[42:43], 1.0 op_sel_hi:[1,0]
	v_pk_add_f32 v[44:45], v[44:45], 1.0 op_sel_hi:[1,0]
	v_rcp_f32_e32 v46, v42
	v_rcp_f32_e32 v47, v43
	v_rcp_f32_e32 v48, v44
	v_rcp_f32_e32 v49, v45
	v_mul_f32_e32 v46, v30, v46
	v_mul_f32_e32 v47, v31, v47
	v_mul_f32_e32 v48, v32, v48
	v_mul_f32_e32 v49, v33, v49
	v_pk_mul_f32 v[34:35], v[34:35], v[46:47]
	v_pk_mul_f32 v[36:37], v[36:37], v[48:49]
	v_cvt_pk_bf16_f32 v66, v34, v35
	v_cvt_pk_bf16_f32 v67, v36, v37
	v_cmp_gt_i32_e32 vcc, s33, v61
	v_cmp_gt_i32_e64 s[2:3], s14, v62
	v_add_u32_e32 v61, 1, v61
	v_add_u32_e32 v62, 1, v62
	s_and_b64 s[2:3], vcc, s[2:3]
	s_and_saveexec_b64 s[4:5], s[2:3]
	global_store_dwordx2 v[58:59], v[66:67], off
	s_or_b64 exec, exec, s[4:5]
	v_add_u32_e32 v60, 1, v60
	v_lshl_add_u64 v[58:59], v[58:59], 0, v[56:57]
	v_cmp_ne_u32_e32 vcc, 0x1100, v60
	s_nop 1
	v_cndmask_b32_e32 v60, 0, v60, vcc
	ds_read2_b64 v[26:29], v63 offset1:32
	v_and_b32_e32 v64, 0xfffffeff, v60
	v_and_b32_e32 v65, 0xffffefff, v60
	v_cmp_eq_u32_e32 vcc, 0, v64
	v_cmp_eq_u32_e64 s[2:3], s33, v65
	v_add_u32_e32 v63, 0x210, v63
	s_nop 0
	v_cndmask_b32_e64 v52, 1.0, 0, vcc
	v_cndmask_b32_e64 v54, 1.0, 0, s[2:3]
	s_waitcnt lgkmcnt(0)
	v_lshlrev_b32_e32 v10, 16, v26
	v_and_b32_e32 v11, 0xffff0000, v26
	v_lshlrev_b32_e32 v12, 16, v27
	v_and_b32_e32 v13, 0xffff0000, v27
	v_lshlrev_b32_e32 v22, 16, v28
	v_and_b32_e32 v23, 0xffff0000, v28
	v_lshlrev_b32_e32 v24, 16, v29
	v_and_b32_e32 v25, 0xffff0000, v29
	v_pk_fma_f32 v[30:31], v[146:147], v[18:19], v[158:159]
	v_pk_fma_f32 v[32:33], v[148:149], v[20:21], v[160:161]
	v_pk_mul_f32 v[38:39], v[52:53], v[14:15] op_sel_hi:[0,1]
	v_pk_mul_f32 v[40:41], v[52:53], v[16:17] op_sel_hi:[0,1]
	v_pk_fma_f32 v[30:31], v[142:143], v[38:39], v[30:31]
	v_pk_fma_f32 v[32:33], v[144:145], v[40:41], v[32:33]
	v_pk_mul_f32 v[38:39], v[54:55], v[22:23] op_sel_hi:[0,1]
	v_pk_mul_f32 v[40:41], v[54:55], v[24:25] op_sel_hi:[0,1]
	v_pk_fma_f32 v[30:31], v[150:151], v[38:39], v[30:31]
	v_pk_fma_f32 v[32:33], v[152:153], v[40:41], v[32:33]
	v_pk_fma_f32 v[34:35], v[134:135], v[6:7], v[154:155]
	v_pk_fma_f32 v[36:37], v[136:137], v[8:9], v[156:157]
	v_pk_mul_f32 v[38:39], v[52:53], v[2:3] op_sel_hi:[0,1]
	v_pk_mul_f32 v[40:41], v[52:53], v[4:5] op_sel_hi:[0,1]
	v_pk_fma_f32 v[34:35], v[130:131], v[38:39], v[34:35]
	v_pk_fma_f32 v[36:37], v[132:133], v[40:41], v[36:37]
	v_pk_mul_f32 v[38:39], v[54:55], v[10:11] op_sel_hi:[0,1]
	v_pk_mul_f32 v[40:41], v[54:55], v[12:13] op_sel_hi:[0,1]
	v_pk_fma_f32 v[34:35], v[138:139], v[38:39], v[34:35]
	v_pk_fma_f32 v[36:37], v[140:141], v[40:41], v[36:37]
	v_mul_f32_e32 v42, 0xbfb8aa3b, v30
	v_exp_f32_e32 v42, v42
	v_mul_f32_e32 v43, 0xbfb8aa3b, v31
	v_exp_f32_e32 v43, v43
	v_mul_f32_e32 v44, 0xbfb8aa3b, v32
	v_exp_f32_e32 v44, v44
	v_mul_f32_e32 v45, 0xbfb8aa3b, v33
	v_exp_f32_e32 v45, v45
	v_pk_add_f32 v[42:43], v[42:43], 1.0 op_sel_hi:[1,0]
	v_pk_add_f32 v[44:45], v[44:45], 1.0 op_sel_hi:[1,0]
	v_rcp_f32_e32 v46, v42
	v_rcp_f32_e32 v47, v43
	v_rcp_f32_e32 v48, v44
	v_rcp_f32_e32 v49, v45
	v_mul_f32_e32 v46, v30, v46
	v_mul_f32_e32 v47, v31, v47
	v_mul_f32_e32 v48, v32, v48
	v_mul_f32_e32 v49, v33, v49
	v_pk_mul_f32 v[34:35], v[34:35], v[46:47]
	v_pk_mul_f32 v[36:37], v[36:37], v[48:49]
	v_cvt_pk_bf16_f32 v66, v34, v35
	v_cvt_pk_bf16_f32 v67, v36, v37
	v_cmp_gt_i32_e32 vcc, s33, v61
	v_cmp_gt_i32_e64 s[2:3], s14, v62
	v_add_u32_e32 v61, 1, v61
	v_add_u32_e32 v62, 1, v62
	s_and_b64 s[2:3], vcc, s[2:3]
	s_and_saveexec_b64 s[4:5], s[2:3]
	global_store_dwordx2 v[58:59], v[66:67], off
	s_or_b64 exec, exec, s[4:5]
	v_add_u32_e32 v60, 1, v60
	v_lshl_add_u64 v[58:59], v[58:59], 0, v[56:57]
	v_cmp_ne_u32_e32 vcc, 0x1100, v60
	s_nop 1
	v_cndmask_b32_e32 v60, 0, v60, vcc
.Lconv_done:
.LBB0_653:
	s_mov_b64 s[2:3], 0
	s_barrier
